# prompt attention: output accumulators stay in home registers in all three bias variants of both key-tile steps (no 16/32 register-pair copies and MFMA drain at the joins); on top of SGU W cache
# speedup vs baseline: 1.0073x; 1.0032x over previous
; template <bool SAMPLE>
; DI void attn_unit(const Params& p, LAS unsigned char* lds, int b, int cp, int hp) {
;     ...
;     for (int j = j_first; j <= j_last; j += 2) {
;         ATT_STEP(j, ka, va_);
;         if (j + 1 <= j_last) ATT_STEP(j + 1, kb_, vb_);
;     }
.Lmy_att_j2:
.LBB0_1190:
	s_add_i32 s13, s13, 2
	v_lshl_add_u64 v[164:165], v[164:165], 0, s[4:5]
	v_lshl_add_u64 v[166:167], v[166:167], 0, s[4:5]
	v_lshl_add_u64 v[168:169], v[168:169], 0, s[4:5]
	v_add_u32_e32 v175, 0xfffffe00, v175
	v_add_u32_e32 v176, 0xffffff80, v176
	v_add_u32_e32 v177, 0xffffff80, v177
	s_andn2_b64 vcc, exec, s[6:7]
	v_add_u32_e32 v178, 0xfffffe00, v178
	s_cbranch_vccz .LBB0_1184

; #define LAS __attribute__((address_space(3)))
; DI unsigned pk2(float lo, float hi) { f32x2 v = {lo, hi}; bf16x2_t b = __builtin_convertvector(v, bf16x2_t); return __builtin_bit_cast(unsigned, b); }
; template <int BM, bool SMASK>
; DI void attn_tile(const LAS unsigned char* kbase, const LAS unsigned char* vbase, const LAS float* bth, int ibase, int h, const bf16x8 (&qf)[4], f32x16& o0, f32x16& o1, float& lsum) {
; #pragma unroll
;     for (int kb = 0; kb < 2; ++kb) {
;         f32x16 pa;
; #pragma unroll
;         for (int r = 0; r < 16; ++r) pa[r] = 0.f;
; #pragma unroll
;         for (int d0 = 0; d0 < 4; ++d0) { const bf16x8 a = *(const LAS bf16x8*)(kbase + kb * 32 * KSTR + d0 * 32); pa = __builtin_amdgcn_mfma_f32_32x32x16_bf16(a, qf[d0], pa, 0, 0, 0); }
;         if (BM == 0) {
;             const float cb = bth[512];
; #pragma unroll
;             for (int r = 0; r < 16; ++r) pa[r] += cb;
;         } else if (BM == 1) {
; #pragma unroll
;             for (int r = 0; r < 16; ++r) { int idx = ibase - 32 * kb - ((r & 3) + 8 * (r >> 2)); idx = idx > 512 ? 512 : idx; pa[r] += bth[idx]; }
;         } else {
;             const LAS float* bp = bth + (ibase - 32 * kb - 27);
; #pragma unroll
;             for (int r = 0; r < 16; ++r) pa[r] += bp[27 - ((r & 3) + 8 * (r >> 2))];
;         }
; #pragma unroll
;         for (int r = 0; r < 16; ++r) pa[r] = __builtin_amdgcn_exp2f(pa[r]);
;         if (SMASK) {
; #pragma unroll
;             for (int r = 0; r < 16; ++r) { const int key = 32 * kb + (r & 3) + 8 * (r >> 2) + 4 * h; if (key >= 16) pa[r] = 0.f; }
;         }
; #pragma unroll
;         for (int r = 0; r < 16; ++r) lsum += pa[r];
; #pragma unroll
;         for (int s = 0; s < 2; ++s) {
;             u32x4 pw; pw.x = pk2(pa[8 * s], pa[8 * s + 1]); pw.y = pk2(pa[8 * s + 2], pa[8 * s + 3]); pw.z = pk2(pa[8 * s + 4], pa[8 * s + 5]); pw.w = pk2(pa[8 * s + 6], pa[8 * s + 7]);
;             const bf16x8 pb = __builtin_bit_cast(bf16x8, pw);
;             const LAS unsigned char* va = vbase + (kb * 32 + 16 * s) * VSTR;
;             { const s16x4 lo = tr_read(va), hi = tr_read(va + 8 * VSTR); o0 = __builtin_amdgcn_mfma_f32_32x32x16_bf16(VFR(lo, hi), pb, o0, 0, 0, 0); }
;             { const s16x4 lo = tr_read(va + 64), hi = tr_read(va + 64 + 8 * VSTR); o1 = __builtin_amdgcn_mfma_f32_32x32x16_bf16(VFR(lo, hi), pb, o1, 0, 0, 0); }
;         }
;     }
; }
.LBB0_1193:
	s_add_i32 s23, s22, s13
	s_cmp_gt_u32 s23, 8
	s_cbranch_scc1 .LBB0_1202
	ds_read_b128 v[130:133], v179 offset:32
	s_cmp_gt_u32 s23, 3
	s_mov_b64 s[6:7], -1
	s_cbranch_scc0 .LBB0_1199
	ds_read_b128 v[142:145], v179
	ds_read_b128 v[138:141], v179 offset:64
	ds_read_b128 v[134:137], v179 offset:96
	s_cmp_lg_u32 s23, 4
	s_cbranch_scc0 .LBB0_1213
	s_waitcnt lgkmcnt(2)
	v_mfma_f32_32x32x16_bf16 v[34:49], v[142:145], v[82:85], 0
	v_add_u32_e32 v181, s20, v178
	v_add_u32_e32 v64, 0x13394, v181
	v_add_u32_e32 v58, 0x133fc, v181
	v_add_u32_e32 v60, 0x133f4, v181
	v_add_u32_e32 v62, 0x133dc, v181
	v_add_u32_e32 v50, 0x133d4, v181
	v_add_u32_e32 v52, 0x133bc, v181
	v_mfma_f32_32x32x16_bf16 v[34:49], v[130:133], v[86:89], v[34:49]
	v_add_u32_e32 v54, 0x133b4, v181
	v_add_u32_e32 v56, 0x1339c, v181
	ds_read2_b32 v[50:51], v50 offset1:1
	ds_read2_b32 v[52:53], v52 offset1:1
	ds_read2_b32 v[54:55], v54 offset1:1
	ds_read2_b32 v[56:57], v56 offset1:1
	ds_read2_b32 v[58:59], v58 offset1:1
	ds_read2_b32 v[60:61], v60 offset1:1
	ds_read2_b32 v[62:63], v62 offset1:1
	ds_read2_b32 v[64:65], v64 offset1:1
	s_waitcnt lgkmcnt(9)
	v_mfma_f32_32x32x16_bf16 v[34:49], v[138:141], v[90:93], v[34:49]
	s_waitcnt lgkmcnt(8)
	v_mfma_f32_32x32x16_bf16 v[34:49], v[134:137], v[94:97], v[34:49]
	s_waitcnt lgkmcnt(3)
	s_nop 10
	v_add_f32_e32 v34, v34, v59
	v_add_f32_e32 v35, v35, v58
	s_waitcnt lgkmcnt(2)
	v_add_f32_e32 v36, v36, v61
	v_add_f32_e32 v37, v37, v60
	s_waitcnt lgkmcnt(1)
	v_add_f32_e32 v38, v38, v63
	v_add_f32_e32 v39, v39, v62
	v_add_f32_e32 v40, v40, v51
	v_add_f32_e32 v41, v41, v50
	v_add_f32_e32 v42, v42, v53
	v_add_f32_e32 v43, v43, v52
	v_exp_f32_e32 v183, v34
	v_exp_f32_e32 v188, v35
	v_exp_f32_e32 v189, v36
	v_exp_f32_e32 v192, v37
	v_exp_f32_e32 v193, v38
	v_exp_f32_e32 v194, v39
	v_exp_f32_e32 v195, v40
	v_exp_f32_e32 v196, v41
	ds_read_b64_tr_b16 v[50:51], v171 offset:17408
	ds_read_b64_tr_b16 v[52:53], v171 offset:19968
	ds_read_b64_tr_b16 v[72:73], v171 offset:20032
	ds_read_b64_tr_b16 v[70:71], v171 offset:17472
	v_add_f32_e32 v55, v44, v55
	v_add_f32_e32 v54, v45, v54
	v_add_f32_e32 v57, v46, v57
	v_add_f32_e32 v56, v47, v56
	s_waitcnt lgkmcnt(4)
	v_add_f32_e32 v58, v48, v65
	v_cvt_pk_bf16_f32 v66, v183, v188
	v_cvt_pk_bf16_f32 v67, v189, v192
	v_cvt_pk_bf16_f32 v68, v193, v194
	v_cvt_pk_bf16_f32 v69, v195, v196
	v_add_f32_e32 v78, v49, v64
	v_exp_f32_e32 v197, v42
	v_exp_f32_e32 v198, v43
	s_waitcnt lgkmcnt(2)
	v_mfma_f32_32x32x16_bf16 v[2:17], v[50:53], v[66:69], v[2:17]
	v_exp_f32_e32 v199, v55
	v_exp_f32_e32 v200, v54
	v_exp_f32_e32 v201, v57
	v_exp_f32_e32 v202, v56
	v_exp_f32_e32 v203, v58
	ds_read_b64_tr_b16 v[74:75], v171 offset:22528
	ds_read_b64_tr_b16 v[76:77], v171 offset:25088
	v_exp_f32_e32 v204, v78
	s_waitcnt lgkmcnt(2)
	v_mfma_f32_32x32x16_bf16 v[18:33], v[70:73], v[66:69], v[18:33]
	ds_read_b64_tr_b16 v[72:73], v171 offset:25152
	ds_read_b64_tr_b16 v[70:71], v171 offset:22592
	v_cvt_pk_bf16_f32 v66, v197, v198
	v_cvt_pk_bf16_f32 v67, v199, v200
	v_cvt_pk_bf16_f32 v68, v201, v202
	v_cvt_pk_bf16_f32 v69, v203, v204
	v_add_f32_e32 v183, v180, v183
	v_add_f32_e32 v183, v188, v183
	s_waitcnt lgkmcnt(2)
	v_mfma_f32_32x32x16_bf16 v[2:17], v[74:77], v[66:69], v[2:17]
	v_add_f32_e32 v183, v189, v183
	v_add_f32_e32 v183, v192, v183
	v_add_f32_e32 v183, v193, v183
	v_add_f32_e32 v183, v194, v183
	v_add_f32_e32 v183, v195, v183
	v_add_f32_e32 v183, v196, v183
	v_add_f32_e32 v183, v197, v183
	s_waitcnt lgkmcnt(0)
	v_mfma_f32_32x32x16_bf16 v[18:33], v[70:73], v[66:69], v[18:33]
	ds_read_b128 v[66:69], v179 offset:8704
	ds_read_b128 v[184:187], v179 offset:8736
	ds_read_b128 v[188:191], v179 offset:8768
	v_add_f32_e32 v183, v198, v183
	v_add_f32_e32 v183, v199, v183
	v_add_f32_e32 v183, v200, v183
	v_add_f32_e32 v183, v201, v183
	v_add_f32_e32 v183, v202, v183
	s_waitcnt lgkmcnt(2)
	v_mfma_f32_32x32x16_bf16 v[66:81], v[66:69], v[82:85], 0
	v_add_f32_e32 v183, v203, v183
	v_add_f32_e32 v183, v204, v183
	s_waitcnt lgkmcnt(1)
	v_mfma_f32_32x32x16_bf16 v[66:81], v[184:187], v[86:89], v[66:81]
	ds_read_b128 v[184:187], v179 offset:8800
	s_waitcnt lgkmcnt(1)
	v_mfma_f32_32x32x16_bf16 v[66:81], v[188:191], v[90:93], v[66:81]
	v_add_u32_e32 v190, 0x13314, v181
	v_add_u32_e32 v188, 0x1335c, v181
	s_waitcnt lgkmcnt(0)
	v_mfma_f32_32x32x16_bf16 v[66:81], v[184:187], v[94:97], v[66:81]
	v_add_u32_e32 v184, 0x1337c, v181
	ds_read2_b32 v[184:185], v184 offset1:1
	v_add_u32_e32 v186, 0x13374, v181
	ds_read2_b32 v[186:187], v186 offset1:1
	ds_read2_b32 v[188:189], v188 offset1:1
	ds_read2_b32 v[190:191], v190 offset1:1
	s_waitcnt lgkmcnt(3)
	s_nop 4
	v_add_f32_e32 v192, v66, v185
	s_waitcnt lgkmcnt(2)
	v_add_f32_e32 v187, v68, v187
	s_waitcnt lgkmcnt(1)
	v_add_f32_e32 v189, v70, v189
	v_add_u32_e32 v66, 0x13354, v181
	v_add_u32_e32 v68, 0x1333c, v181
	v_add_u32_e32 v70, 0x13334, v181
	v_add_f32_e32 v193, v67, v184
	v_add_f32_e32 v186, v69, v186
	v_add_f32_e32 v188, v71, v188
	ds_read2_b32 v[66:67], v66 offset1:1
	v_add_u32_e32 v181, 0x1331c, v181
	ds_read2_b32 v[68:69], v68 offset1:1
	ds_read2_b32 v[70:71], v70 offset1:1
	ds_read2_b32 v[184:185], v181 offset1:1
	s_waitcnt lgkmcnt(3)
	v_add_f32_e32 v67, v72, v67
	s_waitcnt lgkmcnt(1)
	v_add_f32_e32 v71, v76, v71
	v_exp_f32_e32 v76, v192
	v_add_f32_e32 v66, v73, v66
	v_add_f32_e32 v69, v74, v69
	v_add_f32_e32 v68, v75, v68
	v_add_f32_e32 v70, v77, v70
	v_exp_f32_e32 v77, v193
	s_waitcnt lgkmcnt(0)
; #define LAS __attribute__((address_space(3)))
; DI unsigned pk2(float lo, float hi) { f32x2 v = {lo, hi}; bf16x2_t b = __builtin_convertvector(v, bf16x2_t); return __builtin_bit_cast(unsigned, b); }
; template <int BM, bool SMASK>
; DI void attn_tile(const LAS unsigned char* kbase, const LAS unsigned char* vbase, const LAS float* bth, int ibase, int h, const bf16x8 (&qf)[4], f32x16& o0, f32x16& o1, float& lsum) {
; #pragma unroll
;     for (int kb = 0; kb < 2; ++kb) {
;         f32x16 pa;
; #pragma unroll
;         for (int r = 0; r < 16; ++r) pa[r] = 0.f;
; #pragma unroll
;         for (int d0 = 0; d0 < 4; ++d0) { const bf16x8 a = *(const LAS bf16x8*)(kbase + kb * 32 * KSTR + d0 * 32); pa = __builtin_amdgcn_mfma_f32_32x32x16_bf16(a, qf[d0], pa, 0, 0, 0); }
;         if (BM == 0) {
;             const float cb = bth[512];
; #pragma unroll
;             for (int r = 0; r < 16; ++r) pa[r] += cb;
;         } else if (BM == 1) {
; #pragma unroll
;             for (int r = 0; r < 16; ++r) { int idx = ibase - 32 * kb - ((r & 3) + 8 * (r >> 2)); idx = idx > 512 ? 512 : idx; pa[r] += bth[idx]; }
;         } else {
;             const LAS float* bp = bth + (ibase - 32 * kb - 27);
; #pragma unroll
;             for (int r = 0; r < 16; ++r) pa[r] += bp[27 - ((r & 3) + 8 * (r >> 2))];
;         }
; #pragma unroll
;         for (int r = 0; r < 16; ++r) pa[r] = __builtin_amdgcn_exp2f(pa[r]);
;         if (SMASK) {
; #pragma unroll
;             for (int r = 0; r < 16; ++r) { const int key = 32 * kb + (r & 3) + 8 * (r >> 2) + 4 * h; if (key >= 16) pa[r] = 0.f; }
;         }
; #pragma unroll
;         for (int r = 0; r < 16; ++r) lsum += pa[r];
; #pragma unroll
;         for (int s = 0; s < 2; ++s) {
;             u32x4 pw; pw.x = pk2(pa[8 * s], pa[8 * s + 1]); pw.y = pk2(pa[8 * s + 2], pa[8 * s + 3]); pw.z = pk2(pa[8 * s + 4], pa[8 * s + 5]); pw.w = pk2(pa[8 * s + 6], pa[8 * s + 7]);
;             const bf16x8 pb = __builtin_bit_cast(bf16x8, pw);
;             const LAS unsigned char* va = vbase + (kb * 32 + 16 * s) * VSTR;
;             { const s16x4 lo = tr_read(va), hi = tr_read(va + 8 * VSTR); o0 = __builtin_amdgcn_mfma_f32_32x32x16_bf16(VFR(lo, hi), pb, o0, 0, 0, 0); }
;             { const s16x4 lo = tr_read(va + 64), hi = tr_read(va + 64 + 8 * VSTR); o1 = __builtin_amdgcn_mfma_f32_32x32x16_bf16(VFR(lo, hi), pb, o1, 0, 0, 0); }
;         }
;     }
; }
	v_add_f32_e32 v72, v78, v185
	v_add_f32_e32 v73, v79, v184
	v_add_f32_e32 v74, v80, v191
	v_add_f32_e32 v75, v81, v190
	v_exp_f32_e32 v78, v187
	v_exp_f32_e32 v79, v186
	v_exp_f32_e32 v80, v189
	v_exp_f32_e32 v81, v188
	v_exp_f32_e32 v181, v67
	v_exp_f32_e32 v184, v66
	v_exp_f32_e32 v185, v69
	v_exp_f32_e32 v186, v68
	ds_read_b64_tr_b16 v[66:67], v171 offset:27648
	ds_read_b64_tr_b16 v[68:69], v171 offset:30208
	v_exp_f32_e32 v188, v70
	v_add_f32_e32 v70, v183, v76
	v_add_f32_e32 v70, v77, v70
	v_exp_f32_e32 v187, v71
	v_exp_f32_e32 v189, v72
	v_exp_f32_e32 v190, v73
	v_add_f32_e32 v183, v78, v70
	v_cvt_pk_bf16_f32 v70, v76, v77
	v_cvt_pk_bf16_f32 v71, v78, v79
	v_cvt_pk_bf16_f32 v72, v80, v81
	v_cvt_pk_bf16_f32 v73, v181, v184
	v_exp_f32_e32 v191, v74
	v_exp_f32_e32 v192, v75
	s_waitcnt lgkmcnt(0)
	v_mfma_f32_32x32x16_bf16 v[2:17], v[66:69], v[70:73], v[2:17]
	v_add_f32_e32 v66, v79, v183
	v_add_f32_e32 v66, v80, v66
	ds_read_b64_tr_b16 v[76:77], v171 offset:30272
	ds_read_b64_tr_b16 v[74:75], v171 offset:27712
	v_add_f32_e32 v66, v81, v66
	v_add_f32_e32 v66, v181, v66
	v_add_f32_e32 v78, v184, v66
	ds_read_b64_tr_b16 v[66:67], v171 offset:32768
	ds_read_b64_tr_b16 v[68:69], v171 offset:35328
	s_waitcnt lgkmcnt(2)
	v_mfma_f32_32x32x16_bf16 v[18:33], v[74:77], v[70:73], v[18:33]
	v_add_f32_e32 v78, v185, v78
	v_cvt_pk_bf16_f32 v70, v185, v186
	v_cvt_pk_bf16_f32 v71, v187, v188
	v_cvt_pk_bf16_f32 v72, v189, v190
	v_cvt_pk_bf16_f32 v73, v191, v192
	ds_read_b64_tr_b16 v[76:77], v171 offset:35392
	ds_read_b64_tr_b16 v[74:75], v171 offset:32832
	s_waitcnt lgkmcnt(2)
	v_mfma_f32_32x32x16_bf16 v[2:17], v[66:69], v[70:73], v[2:17]
	v_add_f32_e32 v66, v186, v78
	v_add_f32_e32 v66, v187, v66
	v_add_f32_e32 v66, v188, v66
	v_add_f32_e32 v66, v189, v66
	v_add_f32_e32 v66, v190, v66
	v_add_f32_e32 v66, v191, v66
	v_add_f32_e32 v66, v192, v66
	s_waitcnt lgkmcnt(0)
	v_mfma_f32_32x32x16_bf16 v[18:33], v[74:77], v[70:73], v[18:33]
	v_mov_b32_e32 v180, v66
	s_branch .Lmy_att_j1
.LBB0_1197:
	v_add_u32_e32 v181, v170, v176
	s_nop 0
	v_add_u32_e32 v34, 0x300, v181
	v_min_u32_e32 v34, 0x200, v34
	s_nop 6
	v_lshl_add_u32 v50, v34, 2, s21
	s_waitcnt lgkmcnt(2)
	v_mfma_f32_32x32x16_bf16 v[34:49], v[142:145], v[82:85], 0
	v_add_u32_e32 v51, 0x2ff, v181
	v_add_u32_e32 v52, 0x2fe, v181
	v_add_u32_e32 v53, 0x2fd, v181
	v_add_u32_e32 v54, 0x2f8, v181
	v_add_u32_e32 v55, 0x2f7, v181
	v_add_u32_e32 v56, 0x2f6, v181
	v_add_u32_e32 v57, 0x2f5, v181
	v_mfma_f32_32x32x16_bf16 v[34:49], v[130:133], v[86:89], v[34:49]
	v_min_u32_e32 v51, 0x200, v51
	v_min_u32_e32 v52, 0x200, v52
	v_min_u32_e32 v53, 0x200, v53
	v_min_u32_e32 v54, 0x200, v54
	v_min_u32_e32 v55, 0x200, v55
	v_min_u32_e32 v56, 0x200, v56
	v_min_u32_e32 v57, 0x200, v57
	s_waitcnt lgkmcnt(1)
	v_mfma_f32_32x32x16_bf16 v[34:49], v[138:141], v[90:93], v[34:49]
	v_lshl_add_u32 v51, v51, 2, s21
	v_lshl_add_u32 v52, v52, 2, s21
	v_lshl_add_u32 v53, v53, 2, s21
	v_lshl_add_u32 v54, v54, 2, s21
	v_lshl_add_u32 v55, v55, 2, s21
	v_lshl_add_u32 v56, v56, 2, s21
	v_lshl_add_u32 v57, v57, 2, s21
	s_waitcnt lgkmcnt(0)
	v_mfma_f32_32x32x16_bf16 v[34:49], v[134:137], v[94:97], v[34:49]
	ds_read_b32 v50, v50
	ds_read_b32 v51, v51
	ds_read_b32 v52, v52
	ds_read_b32 v53, v53
	ds_read_b32 v54, v54
	ds_read_b32 v55, v55
	ds_read_b32 v56, v56
	ds_read_b32 v57, v57
	s_waitcnt lgkmcnt(7)
	s_nop 2
	v_add_f32_e32 v34, v34, v50
	s_waitcnt lgkmcnt(6)
	v_add_f32_e32 v35, v35, v51
	s_waitcnt lgkmcnt(5)
	v_add_f32_e32 v36, v36, v52
	s_waitcnt lgkmcnt(4)
	v_add_f32_e32 v37, v37, v53
	s_waitcnt lgkmcnt(3)
	v_add_f32_e32 v38, v38, v54
	s_waitcnt lgkmcnt(2)
	v_add_f32_e32 v39, v39, v55
	s_waitcnt lgkmcnt(1)
	v_add_f32_e32 v40, v40, v56
	s_waitcnt lgkmcnt(0)
	v_add_f32_e32 v41, v41, v57
	v_add_u32_e32 v50, 0x2f0, v181
	v_add_u32_e32 v51, 0x2ef, v181
	v_add_u32_e32 v52, 0x2ee, v181
	v_add_u32_e32 v53, 0x2ed, v181
	v_add_u32_e32 v54, 0x2e8, v181
	v_add_u32_e32 v55, 0x2e7, v181
	v_add_u32_e32 v56, 0x2e6, v181
	v_add_u32_e32 v57, 0x2e5, v181
	v_min_u32_e32 v50, 0x200, v50
	v_min_u32_e32 v51, 0x200, v51
	v_min_u32_e32 v52, 0x200, v52
	v_min_u32_e32 v53, 0x200, v53
	v_min_u32_e32 v54, 0x200, v54
	v_min_u32_e32 v55, 0x200, v55
	v_min_u32_e32 v56, 0x200, v56
	v_min_u32_e32 v57, 0x200, v57
	v_lshl_add_u32 v50, v50, 2, s21
	v_lshl_add_u32 v51, v51, 2, s21
	v_lshl_add_u32 v52, v52, 2, s21
	v_lshl_add_u32 v53, v53, 2, s21
	v_lshl_add_u32 v54, v54, 2, s21
	v_lshl_add_u32 v55, v55, 2, s21
	v_lshl_add_u32 v56, v56, 2, s21
	v_lshl_add_u32 v57, v57, 2, s21
	ds_read_b32 v50, v50
	ds_read_b32 v51, v51
	ds_read_b32 v52, v52
	ds_read_b32 v53, v53
	ds_read_b32 v54, v54
	ds_read_b32 v55, v55
	ds_read_b32 v56, v56
	ds_read_b32 v57, v57
	s_waitcnt lgkmcnt(7)
	v_add_f32_e32 v42, v42, v50
	s_waitcnt lgkmcnt(6)
	v_add_f32_e32 v43, v43, v51
	s_waitcnt lgkmcnt(5)
	v_add_f32_e32 v58, v44, v52
	s_waitcnt lgkmcnt(4)
	v_add_f32_e32 v59, v45, v53
	v_exp_f32_e32 v138, v34
	v_exp_f32_e32 v139, v35
	v_exp_f32_e32 v140, v36
	v_exp_f32_e32 v142, v37
	v_exp_f32_e32 v143, v38
	v_exp_f32_e32 v144, v39
	v_exp_f32_e32 v145, v40
	v_exp_f32_e32 v183, v41
	ds_read_b64_tr_b16 v[50:51], v171 offset:17408
	ds_read_b64_tr_b16 v[52:53], v171 offset:19968
	ds_read_b64_tr_b16 v[72:73], v171 offset:20032
	ds_read_b64_tr_b16 v[70:71], v171 offset:17472
	s_waitcnt lgkmcnt(7)
	v_add_f32_e32 v54, v46, v54
	s_waitcnt lgkmcnt(6)
	v_add_f32_e32 v55, v47, v55
	s_waitcnt lgkmcnt(5)
	v_add_f32_e32 v56, v48, v56
	v_cvt_pk_bf16_f32 v66, v138, v139
	v_cvt_pk_bf16_f32 v67, v140, v142
	v_cvt_pk_bf16_f32 v68, v143, v144
	v_cvt_pk_bf16_f32 v69, v145, v183
	s_waitcnt lgkmcnt(4)
; #define LAS __attribute__((address_space(3)))
; DI unsigned pk2(float lo, float hi) { f32x2 v = {lo, hi}; bf16x2_t b = __builtin_convertvector(v, bf16x2_t); return __builtin_bit_cast(unsigned, b); }
; template <int BM, bool SMASK>
; DI void attn_tile(const LAS unsigned char* kbase, const LAS unsigned char* vbase, const LAS float* bth, int ibase, int h, const bf16x8 (&qf)[4], f32x16& o0, f32x16& o1, float& lsum) {
; #pragma unroll
;     for (int kb = 0; kb < 2; ++kb) {
;         f32x16 pa;
; #pragma unroll
;         for (int r = 0; r < 16; ++r) pa[r] = 0.f;
; #pragma unroll
;         for (int d0 = 0; d0 < 4; ++d0) { const bf16x8 a = *(const LAS bf16x8*)(kbase + kb * 32 * KSTR + d0 * 32); pa = __builtin_amdgcn_mfma_f32_32x32x16_bf16(a, qf[d0], pa, 0, 0, 0); }
;         if (BM == 0) {
;             const float cb = bth[512];
; #pragma unroll
;             for (int r = 0; r < 16; ++r) pa[r] += cb;
;         } else if (BM == 1) {
; #pragma unroll
;             for (int r = 0; r < 16; ++r) { int idx = ibase - 32 * kb - ((r & 3) + 8 * (r >> 2)); idx = idx > 512 ? 512 : idx; pa[r] += bth[idx]; }
;         } else {
;             const LAS float* bp = bth + (ibase - 32 * kb - 27);
; #pragma unroll
;             for (int r = 0; r < 16; ++r) pa[r] += bp[27 - ((r & 3) + 8 * (r >> 2))];
;         }
; #pragma unroll
;         for (int r = 0; r < 16; ++r) pa[r] = __builtin_amdgcn_exp2f(pa[r]);
;         if (SMASK) {
; #pragma unroll
;             for (int r = 0; r < 16; ++r) { const int key = 32 * kb + (r & 3) + 8 * (r >> 2) + 4 * h; if (key >= 16) pa[r] = 0.f; }
;         }
; #pragma unroll
;         for (int r = 0; r < 16; ++r) lsum += pa[r];
; #pragma unroll
;         for (int s = 0; s < 2; ++s) {
;             u32x4 pw; pw.x = pk2(pa[8 * s], pa[8 * s + 1]); pw.y = pk2(pa[8 * s + 2], pa[8 * s + 3]); pw.z = pk2(pa[8 * s + 4], pa[8 * s + 5]); pw.w = pk2(pa[8 * s + 6], pa[8 * s + 7]);
;             const bf16x8 pb = __builtin_bit_cast(bf16x8, pw);
;             const LAS unsigned char* va = vbase + (kb * 32 + 16 * s) * VSTR;
;             { const s16x4 lo = tr_read(va), hi = tr_read(va + 8 * VSTR); o0 = __builtin_amdgcn_mfma_f32_32x32x16_bf16(VFR(lo, hi), pb, o0, 0, 0, 0); }
;             { const s16x4 lo = tr_read(va + 64), hi = tr_read(va + 64 + 8 * VSTR); o1 = __builtin_amdgcn_mfma_f32_32x32x16_bf16(VFR(lo, hi), pb, o1, 0, 0, 0); }
;         }
;     }
; }
	v_add_f32_e32 v78, v49, v57
	v_exp_f32_e32 v184, v42
	v_exp_f32_e32 v185, v43
	s_waitcnt lgkmcnt(2)
	v_mfma_f32_32x32x16_bf16 v[2:17], v[50:53], v[66:69], v[2:17]
	v_exp_f32_e32 v186, v58
	v_exp_f32_e32 v187, v59
	v_exp_f32_e32 v188, v54
	v_exp_f32_e32 v189, v55
	v_exp_f32_e32 v190, v56
	ds_read_b64_tr_b16 v[74:75], v171 offset:22528
	ds_read_b64_tr_b16 v[76:77], v171 offset:25088
	v_exp_f32_e32 v191, v78
	s_waitcnt lgkmcnt(2)
	v_mfma_f32_32x32x16_bf16 v[18:33], v[70:73], v[66:69], v[18:33]
	ds_read_b64_tr_b16 v[72:73], v171 offset:25152
	ds_read_b64_tr_b16 v[70:71], v171 offset:22592
	v_cvt_pk_bf16_f32 v66, v184, v185
	v_cvt_pk_bf16_f32 v67, v186, v187
	v_cvt_pk_bf16_f32 v68, v188, v189
	v_cvt_pk_bf16_f32 v69, v190, v191
	v_add_f32_e32 v138, v180, v138
	v_add_f32_e32 v138, v139, v138
	s_waitcnt lgkmcnt(2)
	v_mfma_f32_32x32x16_bf16 v[2:17], v[74:77], v[66:69], v[2:17]
	v_add_f32_e32 v192, v140, v138
	s_waitcnt lgkmcnt(0)
	v_mfma_f32_32x32x16_bf16 v[18:33], v[70:73], v[66:69], v[18:33]
	ds_read_b128 v[66:69], v179 offset:8704
	ds_read_b128 v[134:137], v179 offset:8736
	ds_read_b128 v[138:141], v179 offset:8768
	s_waitcnt lgkmcnt(2)
	v_mfma_f32_32x32x16_bf16 v[66:81], v[66:69], v[82:85], 0
	s_waitcnt lgkmcnt(1)
	v_mfma_f32_32x32x16_bf16 v[66:81], v[134:137], v[86:89], v[66:81]
	v_add_f32_e32 v134, v142, v192
	v_add_f32_e32 v134, v143, v134
	v_add_f32_e32 v134, v144, v134
	v_add_f32_e32 v134, v145, v134
	v_add_f32_e32 v134, v183, v134
	v_add_f32_e32 v142, v184, v134
	ds_read_b128 v[134:137], v179 offset:8800
	s_waitcnt lgkmcnt(1)
	v_mfma_f32_32x32x16_bf16 v[66:81], v[138:141], v[90:93], v[66:81]
	v_add_f32_e32 v138, v185, v142
	v_add_u32_e32 v139, 0x2d8, v181
	v_add_u32_e32 v140, 0x2d7, v181
	v_add_u32_e32 v141, 0x2d6, v181
	v_add_u32_e32 v142, 0x2d5, v181
	v_min_u32_e32 v139, 0x200, v139
	v_min_u32_e32 v140, 0x200, v140
	s_waitcnt lgkmcnt(0)
	v_mfma_f32_32x32x16_bf16 v[66:81], v[134:137], v[94:97], v[66:81]
	v_add_u32_e32 v134, 0x2e0, v181
	v_add_u32_e32 v135, 0x2df, v181
	v_add_u32_e32 v136, 0x2de, v181
	v_add_u32_e32 v137, 0x2dd, v181
	v_min_u32_e32 v134, 0x200, v134
	v_min_u32_e32 v135, 0x200, v135
	v_min_u32_e32 v136, 0x200, v136
	v_min_u32_e32 v137, 0x200, v137
	v_min_u32_e32 v141, 0x200, v141
	v_min_u32_e32 v142, 0x200, v142
	v_lshl_add_u32 v134, v134, 2, s21
	v_lshl_add_u32 v135, v135, 2, s21
	v_lshl_add_u32 v136, v136, 2, s21
	v_lshl_add_u32 v137, v137, 2, s21
	v_lshl_add_u32 v139, v139, 2, s21
	v_lshl_add_u32 v140, v140, 2, s21
	v_lshl_add_u32 v141, v141, 2, s21
	v_lshl_add_u32 v142, v142, 2, s21
	ds_read_b32 v134, v134
	ds_read_b32 v135, v135
	ds_read_b32 v136, v136
	ds_read_b32 v137, v137
	ds_read_b32 v139, v139
	ds_read_b32 v140, v140
	ds_read_b32 v141, v141
	ds_read_b32 v142, v142
	s_waitcnt lgkmcnt(7)
	v_add_f32_e32 v66, v66, v134
	s_waitcnt lgkmcnt(6)
	v_add_f32_e32 v67, v67, v135
	s_waitcnt lgkmcnt(5)
	v_add_f32_e32 v68, v68, v136
	s_waitcnt lgkmcnt(4)
	v_add_f32_e32 v69, v69, v137
	s_waitcnt lgkmcnt(3)
	v_add_f32_e32 v70, v70, v139
	s_waitcnt lgkmcnt(2)
	v_add_f32_e32 v71, v71, v140
	s_waitcnt lgkmcnt(1)
	v_add_f32_e32 v72, v72, v141
	s_waitcnt lgkmcnt(0)
	v_add_f32_e32 v73, v73, v142
	v_add_u32_e32 v134, 0x2d0, v181
	v_add_u32_e32 v135, 0x2cf, v181
	v_add_u32_e32 v136, 0x2ce, v181
	v_add_u32_e32 v137, 0x2cd, v181
	v_add_u32_e32 v139, 0x2c8, v181
	v_add_u32_e32 v140, 0x2c7, v181
	v_add_u32_e32 v141, 0x2c6, v181
	v_add_u32_e32 v142, 0x2c5, v181
	v_min_u32_e32 v134, 0x200, v134
	v_min_u32_e32 v135, 0x200, v135
	v_min_u32_e32 v136, 0x200, v136
	v_min_u32_e32 v137, 0x200, v137
	v_min_u32_e32 v139, 0x200, v139
	v_min_u32_e32 v140, 0x200, v140
	v_min_u32_e32 v141, 0x200, v141
	v_min_u32_e32 v142, 0x200, v142
	v_lshl_add_u32 v134, v134, 2, s21
	v_lshl_add_u32 v135, v135, 2, s21
	v_lshl_add_u32 v136, v136, 2, s21
	v_lshl_add_u32 v137, v137, 2, s21
	v_lshl_add_u32 v139, v139, 2, s21
	v_lshl_add_u32 v140, v140, 2, s21
	v_lshl_add_u32 v141, v141, 2, s21
	v_lshl_add_u32 v142, v142, 2, s21
	ds_read_b32 v134, v134
	ds_read_b32 v135, v135
	ds_read_b32 v136, v136
	ds_read_b32 v137, v137
	ds_read_b32 v139, v139
	ds_read_b32 v140, v140
	ds_read_b32 v141, v141
	ds_read_b32 v142, v142
	v_add_f32_e32 v138, v186, v138
	v_add_f32_e32 v138, v187, v138
	v_add_f32_e32 v138, v188, v138
	s_waitcnt lgkmcnt(7)
	v_add_f32_e32 v74, v74, v134
	v_exp_f32_e32 v134, v66
	v_add_f32_e32 v138, v189, v138
	s_waitcnt lgkmcnt(6)
	v_add_f32_e32 v75, v75, v135
	v_exp_f32_e32 v135, v67
	v_add_f32_e32 v138, v190, v138
	s_waitcnt lgkmcnt(5)
	v_add_f32_e32 v76, v76, v136
	s_waitcnt lgkmcnt(4)
	v_add_f32_e32 v77, v77, v137
	s_waitcnt lgkmcnt(3)
	v_add_f32_e32 v78, v78, v139
	s_waitcnt lgkmcnt(2)
	v_add_f32_e32 v79, v79, v140
	s_waitcnt lgkmcnt(1)
	v_add_f32_e32 v80, v80, v141
	s_waitcnt lgkmcnt(0)
	v_add_f32_e32 v81, v81, v142
	v_exp_f32_e32 v136, v68
	v_exp_f32_e32 v137, v69
	v_exp_f32_e32 v139, v70
	v_exp_f32_e32 v140, v71
	v_exp_f32_e32 v141, v72
	v_exp_f32_e32 v142, v73
	ds_read_b64_tr_b16 v[66:67], v171 offset:27648
	ds_read_b64_tr_b16 v[68:69], v171 offset:30208
	v_add_f32_e32 v138, v191, v138
	v_exp_f32_e32 v143, v74
	v_exp_f32_e32 v144, v75
	v_exp_f32_e32 v145, v76
	v_exp_f32_e32 v181, v77
	ds_read_b64_tr_b16 v[76:77], v171 offset:30272
	ds_read_b64_tr_b16 v[74:75], v171 offset:27712
	v_add_f32_e32 v70, v138, v134
	v_add_f32_e32 v70, v135, v70
	v_add_f32_e32 v138, v136, v70
	v_cvt_pk_bf16_f32 v70, v134, v135
	v_cvt_pk_bf16_f32 v71, v136, v137
	v_cvt_pk_bf16_f32 v72, v139, v140
	v_cvt_pk_bf16_f32 v73, v141, v142
	v_exp_f32_e32 v78, v78
	v_exp_f32_e32 v79, v79
	s_waitcnt lgkmcnt(2)
	v_mfma_f32_32x32x16_bf16 v[2:17], v[66:69], v[70:73], v[2:17]
	v_add_f32_e32 v66, v137, v138
	v_add_f32_e32 v66, v139, v66
	v_add_f32_e32 v66, v140, v66
	v_add_f32_e32 v66, v141, v66
	v_exp_f32_e32 v80, v80
	v_exp_f32_e32 v81, v81
	v_add_f32_e32 v134, v142, v66
	s_waitcnt lgkmcnt(0)
	v_mfma_f32_32x32x16_bf16 v[18:33], v[74:77], v[70:73], v[18:33]
	ds_read_b64_tr_b16 v[66:67], v171 offset:32768
	ds_read_b64_tr_b16 v[68:69], v171 offset:35328
	ds_read_b64_tr_b16 v[76:77], v171 offset:35392
	ds_read_b64_tr_b16 v[74:75], v171 offset:32832
	v_cvt_pk_bf16_f32 v70, v143, v144
	v_cvt_pk_bf16_f32 v71, v145, v181
	v_cvt_pk_bf16_f32 v72, v78, v79
	v_cvt_pk_bf16_f32 v73, v80, v81
	v_add_f32_e32 v134, v143, v134
	s_waitcnt lgkmcnt(2)
	v_mfma_f32_32x32x16_bf16 v[2:17], v[66:69], v[70:73], v[2:17]
	v_add_f32_e32 v66, v144, v134
	v_add_f32_e32 v66, v145, v66
	v_add_f32_e32 v66, v181, v66
	v_add_f32_e32 v66, v78, v66
	v_add_f32_e32 v66, v79, v66
	v_add_f32_e32 v66, v80, v66
	v_add_f32_e32 v66, v81, v66
	s_waitcnt lgkmcnt(0)
	v_mfma_f32_32x32x16_bf16 v[18:33], v[74:77], v[70:73], v[18:33]
	v_mov_b32_e32 v180, v66
	s_branch .Lmy_att_j1

; #define LAS __attribute__((address_space(3)))
; DI unsigned pk2(float lo, float hi) { f32x2 v = {lo, hi}; bf16x2_t b = __builtin_convertvector(v, bf16x2_t); return __builtin_bit_cast(unsigned, b); }
; template <int BM, bool SMASK>
; DI void attn_tile(const LAS unsigned char* kbase, const LAS unsigned char* vbase, const LAS float* bth, int ibase, int h, const bf16x8 (&qf)[4], f32x16& o0, f32x16& o1, float& lsum) {
; #pragma unroll
;     for (int kb = 0; kb < 2; ++kb) {
;         f32x16 pa;
; #pragma unroll
;         for (int r = 0; r < 16; ++r) pa[r] = 0.f;
; #pragma unroll
;         for (int d0 = 0; d0 < 4; ++d0) { const bf16x8 a = *(const LAS bf16x8*)(kbase + kb * 32 * KSTR + d0 * 32); pa = __builtin_amdgcn_mfma_f32_32x32x16_bf16(a, qf[d0], pa, 0, 0, 0); }
;         if (BM == 0) {
;             const float cb = bth[512];
; #pragma unroll
;             for (int r = 0; r < 16; ++r) pa[r] += cb;
;         } else if (BM == 1) {
; #pragma unroll
;             for (int r = 0; r < 16; ++r) { int idx = ibase - 32 * kb - ((r & 3) + 8 * (r >> 2)); idx = idx > 512 ? 512 : idx; pa[r] += bth[idx]; }
;         } else {
;             const LAS float* bp = bth + (ibase - 32 * kb - 27);
; #pragma unroll
;             for (int r = 0; r < 16; ++r) pa[r] += bp[27 - ((r & 3) + 8 * (r >> 2))];
;         }
; #pragma unroll
;         for (int r = 0; r < 16; ++r) pa[r] = __builtin_amdgcn_exp2f(pa[r]);
;         if (SMASK) {
; #pragma unroll
;             for (int r = 0; r < 16; ++r) { const int key = 32 * kb + (r & 3) + 8 * (r >> 2) + 4 * h; if (key >= 16) pa[r] = 0.f; }
;         }
; #pragma unroll
;         for (int r = 0; r < 16; ++r) lsum += pa[r];
; #pragma unroll
;         for (int s = 0; s < 2; ++s) {
;             u32x4 pw; pw.x = pk2(pa[8 * s], pa[8 * s + 1]); pw.y = pk2(pa[8 * s + 2], pa[8 * s + 3]); pw.z = pk2(pa[8 * s + 4], pa[8 * s + 5]); pw.w = pk2(pa[8 * s + 6], pa[8 * s + 7]);
;             const bf16x8 pb = __builtin_bit_cast(bf16x8, pw);
;             const LAS unsigned char* va = vbase + (kb * 32 + 16 * s) * VSTR;
;             { const s16x4 lo = tr_read(va), hi = tr_read(va + 8 * VSTR); o0 = __builtin_amdgcn_mfma_f32_32x32x16_bf16(VFR(lo, hi), pb, o0, 0, 0, 0); }
;             { const s16x4 lo = tr_read(va + 64), hi = tr_read(va + 64 + 8 * VSTR); o1 = __builtin_amdgcn_mfma_f32_32x32x16_bf16(VFR(lo, hi), pb, o1, 0, 0, 0); }
;         }
;     }
; }
.LBB0_1199:
	s_andn2_b64 vcc, exec, s[6:7]
	s_cbranch_vccnz .LBB0_1201
	ds_read_b128 v[34:37], v179
	v_mov_b32_e32 v38, s21
	ds_read_b32 v66, v38 offset:2048
	s_nop 5
	ds_read_b128 v[50:53], v179 offset:64
	ds_read_b128 v[54:57], v179 offset:96
	s_waitcnt lgkmcnt(3)
	v_mfma_f32_32x32x16_bf16 v[34:49], v[34:37], v[82:85], 0
	v_mfma_f32_32x32x16_bf16 v[34:49], v[130:133], v[86:89], v[34:49]
	s_waitcnt lgkmcnt(1)
	v_mfma_f32_32x32x16_bf16 v[34:49], v[50:53], v[90:93], v[34:49]
	ds_read_b64_tr_b16 v[50:51], v171 offset:17408
	ds_read_b64_tr_b16 v[52:53], v171 offset:19968
	ds_read_b64_tr_b16 v[60:61], v171 offset:20032
	ds_read_b64_tr_b16 v[58:59], v171 offset:17472
	ds_read_b128 v[62:65], v179 offset:8704
	s_waitcnt lgkmcnt(5)
	v_mfma_f32_32x32x16_bf16 v[34:49], v[54:57], v[94:97], v[34:49]
	s_nop 11
	v_add_f32_e32 v34, v66, v34
	v_add_f32_e32 v35, v66, v35
	v_add_f32_e32 v36, v66, v36
	v_add_f32_e32 v37, v66, v37
	v_add_f32_e32 v38, v66, v38
	v_add_f32_e32 v39, v66, v39
	v_add_f32_e32 v40, v66, v40
	v_add_f32_e32 v41, v66, v41
	v_exp_f32_e32 v54, v34
	v_exp_f32_e32 v55, v35
	v_exp_f32_e32 v56, v36
	v_exp_f32_e32 v57, v37
	v_exp_f32_e32 v67, v38
	v_exp_f32_e32 v68, v39
	v_exp_f32_e32 v69, v40
	v_exp_f32_e32 v70, v41
	v_cvt_pk_bf16_f32 v34, v54, v55
	v_cvt_pk_bf16_f32 v35, v56, v57
	v_cvt_pk_bf16_f32 v36, v67, v68
	v_cvt_pk_bf16_f32 v37, v69, v70
	v_add_f32_e32 v42, v66, v42
	v_add_f32_e32 v43, v66, v43
	v_add_f32_e32 v44, v66, v44
	v_add_f32_e32 v45, v66, v45
	s_waitcnt lgkmcnt(3)
	v_mfma_f32_32x32x16_bf16 v[2:17], v[50:53], v[34:37], v[2:17]
	v_add_f32_e32 v38, v66, v46
	v_add_f32_e32 v39, v66, v47
	v_add_f32_e32 v40, v66, v48
	v_add_f32_e32 v41, v66, v49
	ds_read_b128 v[50:53], v179 offset:8736
	v_exp_f32_e32 v71, v42
	v_exp_f32_e32 v72, v43
	v_exp_f32_e32 v73, v44
	s_waitcnt lgkmcnt(2)
	v_mfma_f32_32x32x16_bf16 v[18:33], v[58:61], v[34:37], v[18:33]
	v_exp_f32_e32 v58, v45
	v_exp_f32_e32 v74, v38
	v_exp_f32_e32 v75, v39
	v_exp_f32_e32 v76, v40
	v_exp_f32_e32 v77, v41
	v_add_f32_e32 v54, v180, v54
	v_add_f32_e32 v54, v55, v54
	s_waitcnt lgkmcnt(1)
	v_mfma_f32_32x32x16_bf16 v[34:49], v[62:65], v[82:85], 0
	v_add_f32_e32 v54, v56, v54
	v_add_f32_e32 v54, v57, v54
	v_add_f32_e32 v54, v67, v54
	v_add_f32_e32 v54, v68, v54
	v_add_f32_e32 v59, v69, v54
	ds_read_b128 v[54:57], v179 offset:8768
	s_waitcnt lgkmcnt(1)
	v_mfma_f32_32x32x16_bf16 v[34:49], v[50:53], v[86:89], v[34:49]
	v_add_f32_e32 v50, v70, v59
	v_add_f32_e32 v50, v71, v50
	v_add_f32_e32 v50, v72, v50
	v_add_f32_e32 v50, v73, v50
	v_add_f32_e32 v50, v58, v50
	v_add_f32_e32 v59, v74, v50
	ds_read_b128 v[50:53], v179 offset:8800
	s_waitcnt lgkmcnt(1)
	v_mfma_f32_32x32x16_bf16 v[34:49], v[54:57], v[90:93], v[34:49]
	v_add_f32_e32 v54, v75, v59
	v_cvt_pk_bf16_f32 v55, v73, v58
	ds_read_b64_tr_b16 v[58:59], v171 offset:22528
	ds_read_b64_tr_b16 v[60:61], v171 offset:25088
	v_add_f32_e32 v54, v76, v54
	v_add_f32_e32 v62, v77, v54
	v_cvt_pk_bf16_f32 v54, v71, v72
	v_cvt_pk_bf16_f32 v56, v74, v75
	s_waitcnt lgkmcnt(2)
	v_mfma_f32_32x32x16_bf16 v[34:49], v[50:53], v[94:97], v[34:49]
	ds_read_b64_tr_b16 v[52:53], v171 offset:25152
	ds_read_b64_tr_b16 v[50:51], v171 offset:22592
	v_cvt_pk_bf16_f32 v57, v76, v77
	s_waitcnt lgkmcnt(2)
	s_nop 0
	v_mfma_f32_32x32x16_bf16 v[2:17], v[58:61], v[54:57], v[2:17]
	s_nop 5
	v_add_f32_e32 v34, v66, v34
	v_add_f32_e32 v35, v66, v35
	v_add_f32_e32 v36, v66, v36
	v_add_f32_e32 v37, v66, v37
	v_add_f32_e32 v38, v66, v38
	v_add_f32_e32 v39, v66, v39
	v_add_f32_e32 v40, v66, v40
	s_waitcnt lgkmcnt(0)
	v_mfma_f32_32x32x16_bf16 v[18:33], v[50:53], v[54:57], v[18:33]
	v_exp_f32_e32 v50, v34
	v_add_f32_e32 v41, v66, v41
	v_exp_f32_e32 v51, v35
	v_add_f32_e32 v42, v66, v42
	v_add_f32_e32 v43, v66, v43
	v_add_f32_e32 v44, v66, v44
	v_add_f32_e32 v45, v66, v45
	v_exp_f32_e32 v52, v36
	v_exp_f32_e32 v53, v37
	v_exp_f32_e32 v54, v38
	v_exp_f32_e32 v55, v39
	v_exp_f32_e32 v56, v40
	v_exp_f32_e32 v57, v41
	ds_read_b64_tr_b16 v[34:35], v171 offset:27648
	ds_read_b64_tr_b16 v[36:37], v171 offset:30208
	v_exp_f32_e32 v58, v42
	v_exp_f32_e32 v59, v43
	v_exp_f32_e32 v60, v44
	v_exp_f32_e32 v61, v45
	ds_read_b64_tr_b16 v[44:45], v171 offset:30272
	ds_read_b64_tr_b16 v[42:43], v171 offset:27712
	v_add_f32_e32 v38, v62, v50
	v_add_f32_e32 v38, v51, v38
	v_add_f32_e32 v62, v52, v38
	v_cvt_pk_bf16_f32 v38, v50, v51
	v_cvt_pk_bf16_f32 v39, v52, v53
	v_cvt_pk_bf16_f32 v40, v54, v55
	v_cvt_pk_bf16_f32 v41, v56, v57
	v_add_f32_e32 v46, v66, v46
	v_add_f32_e32 v47, v66, v47
	s_waitcnt lgkmcnt(2)
	v_mfma_f32_32x32x16_bf16 v[2:17], v[34:37], v[38:41], v[2:17]
	v_add_f32_e32 v34, v53, v62
	v_add_f32_e32 v34, v54, v34
	v_add_f32_e32 v34, v55, v34
	v_add_f32_e32 v48, v66, v48
	v_add_f32_e32 v49, v66, v49
	v_add_f32_e32 v34, v56, v34
	v_exp_f32_e32 v46, v46
	s_waitcnt lgkmcnt(0)
	v_mfma_f32_32x32x16_bf16 v[18:33], v[42:45], v[38:41], v[18:33]
	v_exp_f32_e32 v47, v47
	v_exp_f32_e32 v48, v48
	v_exp_f32_e32 v49, v49
	v_add_f32_e32 v50, v57, v34
	ds_read_b64_tr_b16 v[34:35], v171 offset:32768
	ds_read_b64_tr_b16 v[36:37], v171 offset:35328
	ds_read_b64_tr_b16 v[44:45], v171 offset:35392
	ds_read_b64_tr_b16 v[42:43], v171 offset:32832
	v_cvt_pk_bf16_f32 v38, v58, v59
	v_cvt_pk_bf16_f32 v39, v60, v61
	v_cvt_pk_bf16_f32 v40, v46, v47
	v_cvt_pk_bf16_f32 v41, v48, v49
	v_add_f32_e32 v50, v58, v50
	s_waitcnt lgkmcnt(2)
	v_mfma_f32_32x32x16_bf16 v[2:17], v[34:37], v[38:41], v[2:17]
	v_add_f32_e32 v34, v59, v50
	v_add_f32_e32 v34, v60, v34
	v_add_f32_e32 v34, v61, v34
	v_add_f32_e32 v34, v46, v34
	v_add_f32_e32 v34, v47, v34
	v_add_f32_e32 v34, v48, v34
	v_add_f32_e32 v66, v49, v34
	s_waitcnt lgkmcnt(0)
	v_mfma_f32_32x32x16_bf16 v[18:33], v[42:45], v[38:41], v[18:33]
	v_mov_b32_e32 v180, v66
	s_branch .Lmy_att_j1

; #define LAS __attribute__((address_space(3)))
; DI unsigned pk2(float lo, float hi) { f32x2 v = {lo, hi}; bf16x2_t b = __builtin_convertvector(v, bf16x2_t); return __builtin_bit_cast(unsigned, b); }
; template <int BM, bool SMASK>
; DI void attn_tile(const LAS unsigned char* kbase, const LAS unsigned char* vbase, const LAS float* bth, int ibase, int h, const bf16x8 (&qf)[4], f32x16& o0, f32x16& o1, float& lsum) {
; #pragma unroll
;     for (int kb = 0; kb < 2; ++kb) {
;         f32x16 pa;
; #pragma unroll
;         for (int r = 0; r < 16; ++r) pa[r] = 0.f;
; #pragma unroll
;         for (int d0 = 0; d0 < 4; ++d0) { const bf16x8 a = *(const LAS bf16x8*)(kbase + kb * 32 * KSTR + d0 * 32); pa = __builtin_amdgcn_mfma_f32_32x32x16_bf16(a, qf[d0], pa, 0, 0, 0); }
;         if (BM == 0) {
;             const float cb = bth[512];
; #pragma unroll
;             for (int r = 0; r < 16; ++r) pa[r] += cb;
;         } else if (BM == 1) {
; #pragma unroll
;             for (int r = 0; r < 16; ++r) { int idx = ibase - 32 * kb - ((r & 3) + 8 * (r >> 2)); idx = idx > 512 ? 512 : idx; pa[r] += bth[idx]; }
;         } else {
;             const LAS float* bp = bth + (ibase - 32 * kb - 27);
; #pragma unroll
;             for (int r = 0; r < 16; ++r) pa[r] += bp[27 - ((r & 3) + 8 * (r >> 2))];
;         }
; #pragma unroll
;         for (int r = 0; r < 16; ++r) pa[r] = __builtin_amdgcn_exp2f(pa[r]);
;         if (SMASK) {
; #pragma unroll
;             for (int r = 0; r < 16; ++r) { const int key = 32 * kb + (r & 3) + 8 * (r >> 2) + 4 * h; if (key >= 16) pa[r] = 0.f; }
;         }
; #pragma unroll
;         for (int r = 0; r < 16; ++r) lsum += pa[r];
; #pragma unroll
;         for (int s = 0; s < 2; ++s) {
;             u32x4 pw; pw.x = pk2(pa[8 * s], pa[8 * s + 1]); pw.y = pk2(pa[8 * s + 2], pa[8 * s + 3]); pw.z = pk2(pa[8 * s + 4], pa[8 * s + 5]); pw.w = pk2(pa[8 * s + 6], pa[8 * s + 7]);
;             const bf16x8 pb = __builtin_bit_cast(bf16x8, pw);
;             const LAS unsigned char* va = vbase + (kb * 32 + 16 * s) * VSTR;
;             { const s16x4 lo = tr_read(va), hi = tr_read(va + 8 * VSTR); o0 = __builtin_amdgcn_mfma_f32_32x32x16_bf16(VFR(lo, hi), pb, o0, 0, 0, 0); }
;             { const s16x4 lo = tr_read(va + 64), hi = tr_read(va + 64 + 8 * VSTR); o1 = __builtin_amdgcn_mfma_f32_32x32x16_bf16(VFR(lo, hi), pb, o1, 0, 0, 0); }
;         }
;     }
; }
.Lmy_att_j1:
.LBB0_1202:
	s_cmp_gt_i32 s13, 7
	s_cselect_b64 s[6:7], -1, 0
	s_and_b64 vcc, exec, s[6:7]
	s_waitcnt lgkmcnt(0)
	s_barrier
	s_cbranch_vccnz .LBB0_1205
	s_cmp_gt_i32 s13, 5
	ds_write_b128 v172, v[114:117]
	ds_write_b128 v173, v[118:121] offset:17408
	ds_write_b128 v172, v[122:125] offset:8704
	ds_write_b128 v173, v[126:129] offset:27648
	s_cbranch_scc1 .LBB0_1205
	v_lshl_add_u64 v[34:35], v[166:167], 0, v[146:147]
	v_add_co_u32_e32 v36, vcc, 0x9a40000, v34
	s_nop 1
	v_addc_co_u32_e32 v37, vcc, 0, v35, vcc
	v_add_co_u32_e32 v34, vcc, 0xba80000, v34
	s_nop 1
	v_addc_co_u32_e32 v35, vcc, 0, v35, vcc
	global_load_dwordx4 v[114:117], v[36:37], off
	global_load_dwordx4 v[118:121], v[34:35], off
	v_lshl_add_u64 v[34:35], v[164:165], 0, v[146:147]
	v_add_co_u32_e32 v36, vcc, 0x9a48000, v34
	s_nop 1
	v_addc_co_u32_e32 v37, vcc, 0, v35, vcc
	v_add_co_u32_e32 v34, vcc, 0xba88000, v34
	s_nop 1
	v_addc_co_u32_e32 v35, vcc, 0, v35, vcc
	global_load_dwordx4 v[122:125], v[36:37], off
	global_load_dwordx4 v[126:129], v[34:35], off
.LBB0_1205:
	s_add_i32 s8, s23, 1
	s_cmp_gt_u32 s8, 8
	s_cbranch_scc1 .LBB0_1190
	ds_read_b128 v[130:133], v179 offset:37920
	s_cmp_gt_u32 s8, 3
	s_mov_b64 s[8:9], -1
	s_cbranch_scc0 .LBB0_1211
	ds_read_b128 v[142:145], v179 offset:37888
	ds_read_b128 v[138:141], v179 offset:37952
	ds_read_b128 v[134:137], v179 offset:37984
	s_cmp_lg_u32 s23, 3
	s_cbranch_scc0 .LBB0_1214
	s_waitcnt lgkmcnt(2)
	v_mfma_f32_32x32x16_bf16 v[34:49], v[142:145], v[82:85], 0
	v_add_u32_e32 v181, s20, v175
	v_add_u32_e32 v64, 0x13294, v181
	v_add_u32_e32 v58, 0x132fc, v181
	v_add_u32_e32 v60, 0x132f4, v181
	v_add_u32_e32 v62, 0x132dc, v181
	v_add_u32_e32 v50, 0x132d4, v181
	v_add_u32_e32 v52, 0x132bc, v181
	v_mfma_f32_32x32x16_bf16 v[34:49], v[130:133], v[86:89], v[34:49]
	v_add_u32_e32 v54, 0x132b4, v181
	v_add_u32_e32 v56, 0x1329c, v181
	ds_read2_b32 v[50:51], v50 offset1:1
	ds_read2_b32 v[52:53], v52 offset1:1
	ds_read2_b32 v[54:55], v54 offset1:1
	ds_read2_b32 v[56:57], v56 offset1:1
	ds_read2_b32 v[58:59], v58 offset1:1
	ds_read2_b32 v[60:61], v60 offset1:1
	ds_read2_b32 v[62:63], v62 offset1:1
	ds_read2_b32 v[64:65], v64 offset1:1
	s_waitcnt lgkmcnt(9)
	v_mfma_f32_32x32x16_bf16 v[34:49], v[138:141], v[90:93], v[34:49]
	s_waitcnt lgkmcnt(8)
	v_mfma_f32_32x32x16_bf16 v[34:49], v[134:137], v[94:97], v[34:49]
	s_waitcnt lgkmcnt(3)
	s_nop 10
	v_add_f32_e32 v34, v34, v59
	v_add_f32_e32 v35, v35, v58
	s_waitcnt lgkmcnt(2)
	v_add_f32_e32 v36, v36, v61
	v_add_f32_e32 v37, v37, v60
	s_waitcnt lgkmcnt(1)
	v_add_f32_e32 v38, v38, v63
	v_add_f32_e32 v39, v39, v62
	v_add_f32_e32 v40, v40, v51
	v_add_f32_e32 v41, v41, v50
	v_add_f32_e32 v42, v42, v53
	v_add_f32_e32 v43, v43, v52
	v_exp_f32_e32 v183, v34
	v_exp_f32_e32 v188, v35
	v_exp_f32_e32 v189, v36
	v_exp_f32_e32 v192, v37
	v_exp_f32_e32 v193, v38
	v_exp_f32_e32 v194, v39
	v_exp_f32_e32 v195, v40
	v_exp_f32_e32 v196, v41
	ds_read_b64_tr_b16 v[50:51], v171 offset:55296
	ds_read_b64_tr_b16 v[52:53], v171 offset:57856
	ds_read_b64_tr_b16 v[72:73], v171 offset:57920
	ds_read_b64_tr_b16 v[70:71], v171 offset:55360
	v_add_f32_e32 v55, v44, v55
	v_add_f32_e32 v54, v45, v54
	v_add_f32_e32 v57, v46, v57
	v_add_f32_e32 v56, v47, v56
	s_waitcnt lgkmcnt(4)
	v_add_f32_e32 v58, v48, v65
	v_cvt_pk_bf16_f32 v66, v183, v188
	v_cvt_pk_bf16_f32 v67, v189, v192
	v_cvt_pk_bf16_f32 v68, v193, v194
	v_cvt_pk_bf16_f32 v69, v195, v196
	v_add_f32_e32 v78, v49, v64
	v_exp_f32_e32 v197, v42
	v_exp_f32_e32 v198, v43
	s_waitcnt lgkmcnt(2)
	v_mfma_f32_32x32x16_bf16 v[2:17], v[50:53], v[66:69], v[2:17]
	v_exp_f32_e32 v199, v55
	v_exp_f32_e32 v200, v54
	v_exp_f32_e32 v201, v57
	v_exp_f32_e32 v202, v56
	v_exp_f32_e32 v203, v58
	ds_read_b64_tr_b16 v[74:75], v171 offset:60416
	ds_read_b64_tr_b16 v[76:77], v171 offset:62976
	v_exp_f32_e32 v204, v78
	s_waitcnt lgkmcnt(2)
	v_mfma_f32_32x32x16_bf16 v[18:33], v[70:73], v[66:69], v[18:33]
	ds_read_b64_tr_b16 v[72:73], v171 offset:63040
	ds_read_b64_tr_b16 v[70:71], v171 offset:60480
	v_cvt_pk_bf16_f32 v66, v197, v198
	v_cvt_pk_bf16_f32 v67, v199, v200
	v_cvt_pk_bf16_f32 v68, v201, v202
	v_cvt_pk_bf16_f32 v69, v203, v204
	v_add_f32_e32 v183, v180, v183
	v_add_f32_e32 v183, v188, v183
	s_waitcnt lgkmcnt(2)
	v_mfma_f32_32x32x16_bf16 v[2:17], v[74:77], v[66:69], v[2:17]
	v_add_f32_e32 v183, v189, v183
	v_add_f32_e32 v183, v192, v183
	v_add_f32_e32 v183, v193, v183
	v_add_f32_e32 v183, v194, v183
	v_add_f32_e32 v183, v195, v183
	v_add_f32_e32 v183, v196, v183
	v_add_f32_e32 v183, v197, v183
	s_waitcnt lgkmcnt(0)
	v_mfma_f32_32x32x16_bf16 v[18:33], v[70:73], v[66:69], v[18:33]
	ds_read_b128 v[66:69], v179 offset:46592
	ds_read_b128 v[184:187], v179 offset:46624
	ds_read_b128 v[188:191], v179 offset:46656
	v_add_f32_e32 v183, v198, v183
	v_add_f32_e32 v183, v199, v183
	v_add_f32_e32 v183, v200, v183
	v_add_f32_e32 v183, v201, v183
	v_add_f32_e32 v183, v202, v183
	s_waitcnt lgkmcnt(2)
	v_mfma_f32_32x32x16_bf16 v[66:81], v[66:69], v[82:85], 0
	v_add_f32_e32 v183, v203, v183
	v_add_f32_e32 v183, v204, v183
	s_waitcnt lgkmcnt(1)
	v_mfma_f32_32x32x16_bf16 v[66:81], v[184:187], v[86:89], v[66:81]
	ds_read_b128 v[184:187], v179 offset:46688
	s_waitcnt lgkmcnt(1)
	v_mfma_f32_32x32x16_bf16 v[66:81], v[188:191], v[90:93], v[66:81]
	v_add_u32_e32 v190, 0x13214, v181
	v_add_u32_e32 v188, 0x1325c, v181
	s_waitcnt lgkmcnt(0)
	v_mfma_f32_32x32x16_bf16 v[66:81], v[184:187], v[94:97], v[66:81]
	v_add_u32_e32 v184, 0x1327c, v181
	ds_read2_b32 v[184:185], v184 offset1:1
	v_add_u32_e32 v186, 0x13274, v181
	ds_read2_b32 v[186:187], v186 offset1:1
	ds_read2_b32 v[188:189], v188 offset1:1
	ds_read2_b32 v[190:191], v190 offset1:1
	s_waitcnt lgkmcnt(3)
; #define LAS __attribute__((address_space(3)))
; DI unsigned pk2(float lo, float hi) { f32x2 v = {lo, hi}; bf16x2_t b = __builtin_convertvector(v, bf16x2_t); return __builtin_bit_cast(unsigned, b); }
; template <int BM, bool SMASK>
; DI void attn_tile(const LAS unsigned char* kbase, const LAS unsigned char* vbase, const LAS float* bth, int ibase, int h, const bf16x8 (&qf)[4], f32x16& o0, f32x16& o1, float& lsum) {
; #pragma unroll
;     for (int kb = 0; kb < 2; ++kb) {
;         f32x16 pa;
; #pragma unroll
;         for (int r = 0; r < 16; ++r) pa[r] = 0.f;
; #pragma unroll
;         for (int d0 = 0; d0 < 4; ++d0) { const bf16x8 a = *(const LAS bf16x8*)(kbase + kb * 32 * KSTR + d0 * 32); pa = __builtin_amdgcn_mfma_f32_32x32x16_bf16(a, qf[d0], pa, 0, 0, 0); }
;         if (BM == 0) {
;             const float cb = bth[512];
; #pragma unroll
;             for (int r = 0; r < 16; ++r) pa[r] += cb;
;         } else if (BM == 1) {
; #pragma unroll
;             for (int r = 0; r < 16; ++r) { int idx = ibase - 32 * kb - ((r & 3) + 8 * (r >> 2)); idx = idx > 512 ? 512 : idx; pa[r] += bth[idx]; }
;         } else {
;             const LAS float* bp = bth + (ibase - 32 * kb - 27);
; #pragma unroll
;             for (int r = 0; r < 16; ++r) pa[r] += bp[27 - ((r & 3) + 8 * (r >> 2))];
;         }
; #pragma unroll
;         for (int r = 0; r < 16; ++r) pa[r] = __builtin_amdgcn_exp2f(pa[r]);
;         if (SMASK) {
; #pragma unroll
;             for (int r = 0; r < 16; ++r) { const int key = 32 * kb + (r & 3) + 8 * (r >> 2) + 4 * h; if (key >= 16) pa[r] = 0.f; }
;         }
; #pragma unroll
;         for (int r = 0; r < 16; ++r) lsum += pa[r];
; #pragma unroll
;         for (int s = 0; s < 2; ++s) {
;             u32x4 pw; pw.x = pk2(pa[8 * s], pa[8 * s + 1]); pw.y = pk2(pa[8 * s + 2], pa[8 * s + 3]); pw.z = pk2(pa[8 * s + 4], pa[8 * s + 5]); pw.w = pk2(pa[8 * s + 6], pa[8 * s + 7]);
;             const bf16x8 pb = __builtin_bit_cast(bf16x8, pw);
;             const LAS unsigned char* va = vbase + (kb * 32 + 16 * s) * VSTR;
;             { const s16x4 lo = tr_read(va), hi = tr_read(va + 8 * VSTR); o0 = __builtin_amdgcn_mfma_f32_32x32x16_bf16(VFR(lo, hi), pb, o0, 0, 0, 0); }
;             { const s16x4 lo = tr_read(va + 64), hi = tr_read(va + 64 + 8 * VSTR); o1 = __builtin_amdgcn_mfma_f32_32x32x16_bf16(VFR(lo, hi), pb, o1, 0, 0, 0); }
;         }
;     }
; }
	s_nop 4
	v_add_f32_e32 v192, v66, v185
	s_waitcnt lgkmcnt(2)
	v_add_f32_e32 v187, v68, v187
	s_waitcnt lgkmcnt(1)
	v_add_f32_e32 v189, v70, v189
	v_add_u32_e32 v66, 0x13254, v181
	v_add_u32_e32 v68, 0x1323c, v181
	v_add_u32_e32 v70, 0x13234, v181
	v_add_f32_e32 v193, v67, v184
	v_add_f32_e32 v186, v69, v186
	v_add_f32_e32 v188, v71, v188
	ds_read2_b32 v[66:67], v66 offset1:1
	v_add_u32_e32 v181, 0x1321c, v181
	ds_read2_b32 v[68:69], v68 offset1:1
	ds_read2_b32 v[70:71], v70 offset1:1
	ds_read2_b32 v[184:185], v181 offset1:1
	s_waitcnt lgkmcnt(3)
	v_add_f32_e32 v67, v72, v67
	s_waitcnt lgkmcnt(1)
	v_add_f32_e32 v71, v76, v71
	v_exp_f32_e32 v76, v192
	v_add_f32_e32 v66, v73, v66
	v_add_f32_e32 v69, v74, v69
	v_add_f32_e32 v68, v75, v68
	v_add_f32_e32 v70, v77, v70
	v_exp_f32_e32 v77, v193
	s_waitcnt lgkmcnt(0)
	v_add_f32_e32 v72, v78, v185
	v_add_f32_e32 v73, v79, v184
	v_add_f32_e32 v74, v80, v191
	v_add_f32_e32 v75, v81, v190
	v_exp_f32_e32 v78, v187
	v_exp_f32_e32 v79, v186
	v_exp_f32_e32 v80, v189
	v_exp_f32_e32 v81, v188
	v_exp_f32_e32 v181, v67
	v_exp_f32_e32 v184, v66
	v_exp_f32_e32 v185, v69
	v_exp_f32_e32 v186, v68
	ds_read_b64_tr_b16 v[66:67], v174 offset:10240
	ds_read_b64_tr_b16 v[68:69], v174 offset:12800
	v_exp_f32_e32 v188, v70
	v_add_f32_e32 v70, v183, v76
	v_add_f32_e32 v70, v77, v70
	v_exp_f32_e32 v187, v71
	v_exp_f32_e32 v189, v72
	v_exp_f32_e32 v190, v73
	v_add_f32_e32 v183, v78, v70
	v_cvt_pk_bf16_f32 v70, v76, v77
	v_cvt_pk_bf16_f32 v71, v78, v79
	v_cvt_pk_bf16_f32 v72, v80, v81
	v_cvt_pk_bf16_f32 v73, v181, v184
	v_exp_f32_e32 v191, v74
	v_exp_f32_e32 v192, v75
	s_waitcnt lgkmcnt(0)
	v_mfma_f32_32x32x16_bf16 v[2:17], v[66:69], v[70:73], v[2:17]
	v_add_f32_e32 v66, v79, v183
	v_add_f32_e32 v66, v80, v66
	ds_read_b64_tr_b16 v[76:77], v174 offset:12864
	ds_read_b64_tr_b16 v[74:75], v174 offset:10304
	v_add_f32_e32 v66, v81, v66
	v_add_f32_e32 v66, v181, v66
	v_add_f32_e32 v78, v184, v66
	ds_read_b64_tr_b16 v[66:67], v174 offset:15360
	ds_read_b64_tr_b16 v[68:69], v174 offset:17920
	s_waitcnt lgkmcnt(2)
	v_mfma_f32_32x32x16_bf16 v[18:33], v[74:77], v[70:73], v[18:33]
	v_add_f32_e32 v78, v185, v78
	v_cvt_pk_bf16_f32 v70, v185, v186
	v_cvt_pk_bf16_f32 v71, v187, v188
	v_cvt_pk_bf16_f32 v72, v189, v190
	v_cvt_pk_bf16_f32 v73, v191, v192
	ds_read_b64_tr_b16 v[76:77], v174 offset:17984
	ds_read_b64_tr_b16 v[74:75], v174 offset:15424
	s_waitcnt lgkmcnt(2)
	v_mfma_f32_32x32x16_bf16 v[2:17], v[66:69], v[70:73], v[2:17]
	v_add_f32_e32 v66, v186, v78
	v_add_f32_e32 v66, v187, v66
	v_add_f32_e32 v66, v188, v66
	v_add_f32_e32 v66, v189, v66
	v_add_f32_e32 v66, v190, v66
	v_add_f32_e32 v66, v191, v66
	v_add_f32_e32 v66, v192, v66
	s_waitcnt lgkmcnt(0)
	v_mfma_f32_32x32x16_bf16 v[18:33], v[74:77], v[70:73], v[18:33]
	v_mov_b32_e32 v180, v66
	s_branch .Lmy_att_j2
.LBB0_1209:
	v_add_u32_e32 v181, v170, v177
	s_nop 0
	v_add_u32_e32 v34, 0x2c0, v181
	v_min_u32_e32 v34, 0x200, v34
	s_nop 6
	v_lshl_add_u32 v50, v34, 2, s21
	s_waitcnt lgkmcnt(2)
	v_mfma_f32_32x32x16_bf16 v[34:49], v[142:145], v[82:85], 0
	v_add_u32_e32 v51, 0x2bf, v181
	v_add_u32_e32 v52, 0x2be, v181
	v_add_u32_e32 v53, 0x2bd, v181
	v_add_u32_e32 v54, 0x2b8, v181
	v_add_u32_e32 v55, 0x2b7, v181
	v_add_u32_e32 v56, 0x2b6, v181
	v_add_u32_e32 v57, 0x2b5, v181
	v_mfma_f32_32x32x16_bf16 v[34:49], v[130:133], v[86:89], v[34:49]
	v_min_u32_e32 v51, 0x200, v51
	v_min_u32_e32 v52, 0x200, v52
	v_min_u32_e32 v53, 0x200, v53
	v_min_u32_e32 v54, 0x200, v54
	v_min_u32_e32 v55, 0x200, v55
	v_min_u32_e32 v56, 0x200, v56
	v_min_u32_e32 v57, 0x200, v57
	s_waitcnt lgkmcnt(1)
	v_mfma_f32_32x32x16_bf16 v[34:49], v[138:141], v[90:93], v[34:49]
	v_lshl_add_u32 v51, v51, 2, s21
	v_lshl_add_u32 v52, v52, 2, s21
	v_lshl_add_u32 v53, v53, 2, s21
	v_lshl_add_u32 v54, v54, 2, s21
	v_lshl_add_u32 v55, v55, 2, s21
	v_lshl_add_u32 v56, v56, 2, s21
	v_lshl_add_u32 v57, v57, 2, s21
	s_waitcnt lgkmcnt(0)
	v_mfma_f32_32x32x16_bf16 v[34:49], v[134:137], v[94:97], v[34:49]
	ds_read_b32 v50, v50
	ds_read_b32 v51, v51
	ds_read_b32 v52, v52
	ds_read_b32 v53, v53
	ds_read_b32 v54, v54
	ds_read_b32 v55, v55
	ds_read_b32 v56, v56
	ds_read_b32 v57, v57
	s_waitcnt lgkmcnt(7)
	s_nop 2
	v_add_f32_e32 v34, v34, v50
	s_waitcnt lgkmcnt(6)
	v_add_f32_e32 v35, v35, v51
	s_waitcnt lgkmcnt(5)
	v_add_f32_e32 v36, v36, v52
	s_waitcnt lgkmcnt(4)
	v_add_f32_e32 v37, v37, v53
	s_waitcnt lgkmcnt(3)
	v_add_f32_e32 v38, v38, v54
	s_waitcnt lgkmcnt(2)
	v_add_f32_e32 v39, v39, v55
	s_waitcnt lgkmcnt(1)
	v_add_f32_e32 v40, v40, v56
	s_waitcnt lgkmcnt(0)
	v_add_f32_e32 v41, v41, v57
	v_add_u32_e32 v50, 0x2b0, v181
	v_add_u32_e32 v51, 0x2af, v181
	v_add_u32_e32 v52, 0x2ae, v181
	v_add_u32_e32 v53, 0x2ad, v181
	v_add_u32_e32 v54, 0x2a8, v181
	v_add_u32_e32 v55, 0x2a7, v181
	v_add_u32_e32 v56, 0x2a6, v181
	v_add_u32_e32 v57, 0x2a5, v181
	v_min_u32_e32 v50, 0x200, v50
	v_min_u32_e32 v51, 0x200, v51
	v_min_u32_e32 v52, 0x200, v52
	v_min_u32_e32 v53, 0x200, v53
	v_min_u32_e32 v54, 0x200, v54
	v_min_u32_e32 v55, 0x200, v55
	v_min_u32_e32 v56, 0x200, v56
	v_min_u32_e32 v57, 0x200, v57
	v_lshl_add_u32 v50, v50, 2, s21
	v_lshl_add_u32 v51, v51, 2, s21
	v_lshl_add_u32 v52, v52, 2, s21
	v_lshl_add_u32 v53, v53, 2, s21
	v_lshl_add_u32 v54, v54, 2, s21
	v_lshl_add_u32 v55, v55, 2, s21
	v_lshl_add_u32 v56, v56, 2, s21
	v_lshl_add_u32 v57, v57, 2, s21
	ds_read_b32 v50, v50
	ds_read_b32 v51, v51
	ds_read_b32 v52, v52
	ds_read_b32 v53, v53
	ds_read_b32 v54, v54
	ds_read_b32 v55, v55
	ds_read_b32 v56, v56
	ds_read_b32 v57, v57
	s_waitcnt lgkmcnt(7)
	v_add_f32_e32 v42, v42, v50
	s_waitcnt lgkmcnt(6)
	v_add_f32_e32 v43, v43, v51
	s_waitcnt lgkmcnt(5)
; #define LAS __attribute__((address_space(3)))
; DI unsigned pk2(float lo, float hi) { f32x2 v = {lo, hi}; bf16x2_t b = __builtin_convertvector(v, bf16x2_t); return __builtin_bit_cast(unsigned, b); }
; template <int BM, bool SMASK>
; DI void attn_tile(const LAS unsigned char* kbase, const LAS unsigned char* vbase, const LAS float* bth, int ibase, int h, const bf16x8 (&qf)[4], f32x16& o0, f32x16& o1, float& lsum) {
; #pragma unroll
;     for (int kb = 0; kb < 2; ++kb) {
;         f32x16 pa;
; #pragma unroll
;         for (int r = 0; r < 16; ++r) pa[r] = 0.f;
; #pragma unroll
;         for (int d0 = 0; d0 < 4; ++d0) { const bf16x8 a = *(const LAS bf16x8*)(kbase + kb * 32 * KSTR + d0 * 32); pa = __builtin_amdgcn_mfma_f32_32x32x16_bf16(a, qf[d0], pa, 0, 0, 0); }
;         if (BM == 0) {
;             const float cb = bth[512];
; #pragma unroll
;             for (int r = 0; r < 16; ++r) pa[r] += cb;
;         } else if (BM == 1) {
; #pragma unroll
;             for (int r = 0; r < 16; ++r) { int idx = ibase - 32 * kb - ((r & 3) + 8 * (r >> 2)); idx = idx > 512 ? 512 : idx; pa[r] += bth[idx]; }
;         } else {
;             const LAS float* bp = bth + (ibase - 32 * kb - 27);
; #pragma unroll
;             for (int r = 0; r < 16; ++r) pa[r] += bp[27 - ((r & 3) + 8 * (r >> 2))];
;         }
; #pragma unroll
;         for (int r = 0; r < 16; ++r) pa[r] = __builtin_amdgcn_exp2f(pa[r]);
;         if (SMASK) {
; #pragma unroll
;             for (int r = 0; r < 16; ++r) { const int key = 32 * kb + (r & 3) + 8 * (r >> 2) + 4 * h; if (key >= 16) pa[r] = 0.f; }
;         }
; #pragma unroll
;         for (int r = 0; r < 16; ++r) lsum += pa[r];
; #pragma unroll
;         for (int s = 0; s < 2; ++s) {
;             u32x4 pw; pw.x = pk2(pa[8 * s], pa[8 * s + 1]); pw.y = pk2(pa[8 * s + 2], pa[8 * s + 3]); pw.z = pk2(pa[8 * s + 4], pa[8 * s + 5]); pw.w = pk2(pa[8 * s + 6], pa[8 * s + 7]);
;             const bf16x8 pb = __builtin_bit_cast(bf16x8, pw);
;             const LAS unsigned char* va = vbase + (kb * 32 + 16 * s) * VSTR;
;             { const s16x4 lo = tr_read(va), hi = tr_read(va + 8 * VSTR); o0 = __builtin_amdgcn_mfma_f32_32x32x16_bf16(VFR(lo, hi), pb, o0, 0, 0, 0); }
;             { const s16x4 lo = tr_read(va + 64), hi = tr_read(va + 64 + 8 * VSTR); o1 = __builtin_amdgcn_mfma_f32_32x32x16_bf16(VFR(lo, hi), pb, o1, 0, 0, 0); }
;         }
;     }
; }
	v_add_f32_e32 v58, v44, v52
	s_waitcnt lgkmcnt(4)
	v_add_f32_e32 v59, v45, v53
	v_exp_f32_e32 v138, v34
	v_exp_f32_e32 v139, v35
	v_exp_f32_e32 v140, v36
	v_exp_f32_e32 v142, v37
	v_exp_f32_e32 v143, v38
	v_exp_f32_e32 v144, v39
	v_exp_f32_e32 v145, v40
	v_exp_f32_e32 v183, v41
	ds_read_b64_tr_b16 v[50:51], v171 offset:55296
	ds_read_b64_tr_b16 v[52:53], v171 offset:57856
	ds_read_b64_tr_b16 v[72:73], v171 offset:57920
	ds_read_b64_tr_b16 v[70:71], v171 offset:55360
	s_waitcnt lgkmcnt(7)
	v_add_f32_e32 v54, v46, v54
	s_waitcnt lgkmcnt(6)
	v_add_f32_e32 v55, v47, v55
	s_waitcnt lgkmcnt(5)
	v_add_f32_e32 v56, v48, v56
	v_cvt_pk_bf16_f32 v66, v138, v139
	v_cvt_pk_bf16_f32 v67, v140, v142
	v_cvt_pk_bf16_f32 v68, v143, v144
	v_cvt_pk_bf16_f32 v69, v145, v183
	s_waitcnt lgkmcnt(4)
	v_add_f32_e32 v78, v49, v57
	v_exp_f32_e32 v184, v42
	v_exp_f32_e32 v185, v43
	s_waitcnt lgkmcnt(2)
	v_mfma_f32_32x32x16_bf16 v[2:17], v[50:53], v[66:69], v[2:17]
	v_exp_f32_e32 v186, v58
	v_exp_f32_e32 v187, v59
	v_exp_f32_e32 v188, v54
	v_exp_f32_e32 v189, v55
	v_exp_f32_e32 v190, v56
	ds_read_b64_tr_b16 v[74:75], v171 offset:60416
	ds_read_b64_tr_b16 v[76:77], v171 offset:62976
	v_exp_f32_e32 v191, v78
	s_waitcnt lgkmcnt(2)
	v_mfma_f32_32x32x16_bf16 v[18:33], v[70:73], v[66:69], v[18:33]
	ds_read_b64_tr_b16 v[72:73], v171 offset:63040
	ds_read_b64_tr_b16 v[70:71], v171 offset:60480
	v_cvt_pk_bf16_f32 v66, v184, v185
	v_cvt_pk_bf16_f32 v67, v186, v187
	v_cvt_pk_bf16_f32 v68, v188, v189
	v_cvt_pk_bf16_f32 v69, v190, v191
	v_add_f32_e32 v138, v180, v138
	v_add_f32_e32 v138, v139, v138
	s_waitcnt lgkmcnt(2)
	v_mfma_f32_32x32x16_bf16 v[2:17], v[74:77], v[66:69], v[2:17]
	v_add_f32_e32 v192, v140, v138
	s_waitcnt lgkmcnt(0)
	v_mfma_f32_32x32x16_bf16 v[18:33], v[70:73], v[66:69], v[18:33]
	ds_read_b128 v[66:69], v179 offset:46592
	ds_read_b128 v[134:137], v179 offset:46624
	ds_read_b128 v[138:141], v179 offset:46656
	s_waitcnt lgkmcnt(2)
	v_mfma_f32_32x32x16_bf16 v[66:81], v[66:69], v[82:85], 0
	s_waitcnt lgkmcnt(1)
	v_mfma_f32_32x32x16_bf16 v[66:81], v[134:137], v[86:89], v[66:81]
	v_add_f32_e32 v134, v142, v192
	v_add_f32_e32 v134, v143, v134
	v_add_f32_e32 v134, v144, v134
	v_add_f32_e32 v134, v145, v134
	v_add_f32_e32 v134, v183, v134
	v_add_f32_e32 v142, v184, v134
	ds_read_b128 v[134:137], v179 offset:46688
	s_waitcnt lgkmcnt(1)
	v_mfma_f32_32x32x16_bf16 v[66:81], v[138:141], v[90:93], v[66:81]
	v_add_f32_e32 v138, v185, v142
	v_add_u32_e32 v139, 0x298, v181
	v_add_u32_e32 v140, 0x297, v181
	v_add_u32_e32 v141, 0x296, v181
	v_add_u32_e32 v142, 0x295, v181
	v_min_u32_e32 v139, 0x200, v139
	v_min_u32_e32 v140, 0x200, v140
	s_waitcnt lgkmcnt(0)
	v_mfma_f32_32x32x16_bf16 v[66:81], v[134:137], v[94:97], v[66:81]
	v_add_u32_e32 v134, 0x2a0, v181
	v_add_u32_e32 v135, 0x29f, v181
	v_add_u32_e32 v136, 0x29e, v181
	v_add_u32_e32 v137, 0x29d, v181
	v_min_u32_e32 v134, 0x200, v134
	v_min_u32_e32 v135, 0x200, v135
	v_min_u32_e32 v136, 0x200, v136
	v_min_u32_e32 v137, 0x200, v137
	v_min_u32_e32 v141, 0x200, v141
	v_min_u32_e32 v142, 0x200, v142
	v_lshl_add_u32 v134, v134, 2, s21
	v_lshl_add_u32 v135, v135, 2, s21
	v_lshl_add_u32 v136, v136, 2, s21
	v_lshl_add_u32 v137, v137, 2, s21
	v_lshl_add_u32 v139, v139, 2, s21
	v_lshl_add_u32 v140, v140, 2, s21
	v_lshl_add_u32 v141, v141, 2, s21
	v_lshl_add_u32 v142, v142, 2, s21
	ds_read_b32 v134, v134
	ds_read_b32 v135, v135
	ds_read_b32 v136, v136
	ds_read_b32 v137, v137
	ds_read_b32 v139, v139
	ds_read_b32 v140, v140
	ds_read_b32 v141, v141
	ds_read_b32 v142, v142
	s_waitcnt lgkmcnt(7)
	v_add_f32_e32 v66, v66, v134
	s_waitcnt lgkmcnt(6)
	v_add_f32_e32 v67, v67, v135
	s_waitcnt lgkmcnt(5)
	v_add_f32_e32 v68, v68, v136
	s_waitcnt lgkmcnt(4)
	v_add_f32_e32 v69, v69, v137
	s_waitcnt lgkmcnt(3)
; #define LAS __attribute__((address_space(3)))
; DI unsigned pk2(float lo, float hi) { f32x2 v = {lo, hi}; bf16x2_t b = __builtin_convertvector(v, bf16x2_t); return __builtin_bit_cast(unsigned, b); }
; template <int BM, bool SMASK>
; DI void attn_tile(const LAS unsigned char* kbase, const LAS unsigned char* vbase, const LAS float* bth, int ibase, int h, const bf16x8 (&qf)[4], f32x16& o0, f32x16& o1, float& lsum) {
; #pragma unroll
;     for (int kb = 0; kb < 2; ++kb) {
;         f32x16 pa;
; #pragma unroll
;         for (int r = 0; r < 16; ++r) pa[r] = 0.f;
; #pragma unroll
;         for (int d0 = 0; d0 < 4; ++d0) { const bf16x8 a = *(const LAS bf16x8*)(kbase + kb * 32 * KSTR + d0 * 32); pa = __builtin_amdgcn_mfma_f32_32x32x16_bf16(a, qf[d0], pa, 0, 0, 0); }
;         if (BM == 0) {
;             const float cb = bth[512];
; #pragma unroll
;             for (int r = 0; r < 16; ++r) pa[r] += cb;
;         } else if (BM == 1) {
; #pragma unroll
;             for (int r = 0; r < 16; ++r) { int idx = ibase - 32 * kb - ((r & 3) + 8 * (r >> 2)); idx = idx > 512 ? 512 : idx; pa[r] += bth[idx]; }
;         } else {
;             const LAS float* bp = bth + (ibase - 32 * kb - 27);
; #pragma unroll
;             for (int r = 0; r < 16; ++r) pa[r] += bp[27 - ((r & 3) + 8 * (r >> 2))];
;         }
; #pragma unroll
;         for (int r = 0; r < 16; ++r) pa[r] = __builtin_amdgcn_exp2f(pa[r]);
;         if (SMASK) {
; #pragma unroll
;             for (int r = 0; r < 16; ++r) { const int key = 32 * kb + (r & 3) + 8 * (r >> 2) + 4 * h; if (key >= 16) pa[r] = 0.f; }
;         }
; #pragma unroll
;         for (int r = 0; r < 16; ++r) lsum += pa[r];
; #pragma unroll
;         for (int s = 0; s < 2; ++s) {
;             u32x4 pw; pw.x = pk2(pa[8 * s], pa[8 * s + 1]); pw.y = pk2(pa[8 * s + 2], pa[8 * s + 3]); pw.z = pk2(pa[8 * s + 4], pa[8 * s + 5]); pw.w = pk2(pa[8 * s + 6], pa[8 * s + 7]);
;             const bf16x8 pb = __builtin_bit_cast(bf16x8, pw);
;             const LAS unsigned char* va = vbase + (kb * 32 + 16 * s) * VSTR;
;             { const s16x4 lo = tr_read(va), hi = tr_read(va + 8 * VSTR); o0 = __builtin_amdgcn_mfma_f32_32x32x16_bf16(VFR(lo, hi), pb, o0, 0, 0, 0); }
;             { const s16x4 lo = tr_read(va + 64), hi = tr_read(va + 64 + 8 * VSTR); o1 = __builtin_amdgcn_mfma_f32_32x32x16_bf16(VFR(lo, hi), pb, o1, 0, 0, 0); }
;         }
;     }
; }
	v_add_f32_e32 v70, v70, v139
	s_waitcnt lgkmcnt(2)
	v_add_f32_e32 v71, v71, v140
	s_waitcnt lgkmcnt(1)
	v_add_f32_e32 v72, v72, v141
	s_waitcnt lgkmcnt(0)
	v_add_f32_e32 v73, v73, v142
	v_add_u32_e32 v134, 0x290, v181
	v_add_u32_e32 v135, 0x28f, v181
	v_add_u32_e32 v136, 0x28e, v181
	v_add_u32_e32 v137, 0x28d, v181
	v_add_u32_e32 v139, 0x288, v181
	v_add_u32_e32 v140, 0x287, v181
	v_add_u32_e32 v141, 0x286, v181
	v_add_u32_e32 v142, 0x285, v181
	v_min_u32_e32 v134, 0x200, v134
	v_min_u32_e32 v135, 0x200, v135
	v_min_u32_e32 v136, 0x200, v136
	v_min_u32_e32 v137, 0x200, v137
	v_min_u32_e32 v139, 0x200, v139
	v_min_u32_e32 v140, 0x200, v140
	v_min_u32_e32 v141, 0x200, v141
	v_min_u32_e32 v142, 0x200, v142
	v_lshl_add_u32 v134, v134, 2, s21
	v_lshl_add_u32 v135, v135, 2, s21
	v_lshl_add_u32 v136, v136, 2, s21
	v_lshl_add_u32 v137, v137, 2, s21
	v_lshl_add_u32 v139, v139, 2, s21
	v_lshl_add_u32 v140, v140, 2, s21
	v_lshl_add_u32 v141, v141, 2, s21
	v_lshl_add_u32 v142, v142, 2, s21
	ds_read_b32 v134, v134
	ds_read_b32 v135, v135
	ds_read_b32 v136, v136
	ds_read_b32 v137, v137
	ds_read_b32 v139, v139
	ds_read_b32 v140, v140
	ds_read_b32 v141, v141
	ds_read_b32 v142, v142
	v_add_f32_e32 v138, v186, v138
	v_add_f32_e32 v138, v187, v138
	v_add_f32_e32 v138, v188, v138
	s_waitcnt lgkmcnt(7)
	v_add_f32_e32 v74, v74, v134
	v_exp_f32_e32 v134, v66
	v_add_f32_e32 v138, v189, v138
	s_waitcnt lgkmcnt(6)
	v_add_f32_e32 v75, v75, v135
	v_exp_f32_e32 v135, v67
	v_add_f32_e32 v138, v190, v138
	s_waitcnt lgkmcnt(5)
	v_add_f32_e32 v76, v76, v136
	s_waitcnt lgkmcnt(4)
	v_add_f32_e32 v77, v77, v137
	s_waitcnt lgkmcnt(3)
	v_add_f32_e32 v78, v78, v139
	s_waitcnt lgkmcnt(2)
	v_add_f32_e32 v79, v79, v140
	s_waitcnt lgkmcnt(1)
	v_add_f32_e32 v80, v80, v141
	s_waitcnt lgkmcnt(0)
	v_add_f32_e32 v81, v81, v142
	v_exp_f32_e32 v136, v68
	v_exp_f32_e32 v137, v69
	v_exp_f32_e32 v139, v70
	v_exp_f32_e32 v140, v71
	v_exp_f32_e32 v141, v72
	v_exp_f32_e32 v142, v73
	ds_read_b64_tr_b16 v[66:67], v174 offset:10240
	ds_read_b64_tr_b16 v[68:69], v174 offset:12800
	v_add_f32_e32 v138, v191, v138
	v_exp_f32_e32 v143, v74
	v_exp_f32_e32 v144, v75
	v_exp_f32_e32 v145, v76
	v_exp_f32_e32 v181, v77
	ds_read_b64_tr_b16 v[76:77], v174 offset:12864
	ds_read_b64_tr_b16 v[74:75], v174 offset:10304
	v_add_f32_e32 v70, v138, v134
	v_add_f32_e32 v70, v135, v70
	v_add_f32_e32 v138, v136, v70
	v_cvt_pk_bf16_f32 v70, v134, v135
	v_cvt_pk_bf16_f32 v71, v136, v137
	v_cvt_pk_bf16_f32 v72, v139, v140
	v_cvt_pk_bf16_f32 v73, v141, v142
	v_exp_f32_e32 v78, v78
	v_exp_f32_e32 v79, v79
	s_waitcnt lgkmcnt(2)
	v_mfma_f32_32x32x16_bf16 v[2:17], v[66:69], v[70:73], v[2:17]
	v_add_f32_e32 v66, v137, v138
	v_add_f32_e32 v66, v139, v66
	v_add_f32_e32 v66, v140, v66
	v_add_f32_e32 v66, v141, v66
	v_exp_f32_e32 v80, v80
	v_exp_f32_e32 v81, v81
	v_add_f32_e32 v134, v142, v66
	s_waitcnt lgkmcnt(0)
	v_mfma_f32_32x32x16_bf16 v[18:33], v[74:77], v[70:73], v[18:33]
	ds_read_b64_tr_b16 v[66:67], v174 offset:15360
	ds_read_b64_tr_b16 v[68:69], v174 offset:17920
	ds_read_b64_tr_b16 v[76:77], v174 offset:17984
	ds_read_b64_tr_b16 v[74:75], v174 offset:15424
	v_cvt_pk_bf16_f32 v70, v143, v144
	v_cvt_pk_bf16_f32 v71, v145, v181
	v_cvt_pk_bf16_f32 v72, v78, v79
	v_cvt_pk_bf16_f32 v73, v80, v81
	v_add_f32_e32 v134, v143, v134
	s_waitcnt lgkmcnt(2)
	v_mfma_f32_32x32x16_bf16 v[2:17], v[66:69], v[70:73], v[2:17]
	v_add_f32_e32 v66, v144, v134
	v_add_f32_e32 v66, v145, v66
	v_add_f32_e32 v66, v181, v66
	v_add_f32_e32 v66, v78, v66
	v_add_f32_e32 v66, v79, v66
	v_add_f32_e32 v66, v80, v66
	v_add_f32_e32 v66, v81, v66
	s_waitcnt lgkmcnt(0)
	v_mfma_f32_32x32x16_bf16 v[18:33], v[74:77], v[70:73], v[18:33]
	v_mov_b32_e32 v180, v66
	s_branch .Lmy_att_j2

; #define LAS __attribute__((address_space(3)))
; DI unsigned pk2(float lo, float hi) { f32x2 v = {lo, hi}; bf16x2_t b = __builtin_convertvector(v, bf16x2_t); return __builtin_bit_cast(unsigned, b); }
; template <int BM, bool SMASK>
; DI void attn_tile(const LAS unsigned char* kbase, const LAS unsigned char* vbase, const LAS float* bth, int ibase, int h, const bf16x8 (&qf)[4], f32x16& o0, f32x16& o1, float& lsum) {
; #pragma unroll
;     for (int kb = 0; kb < 2; ++kb) {
;         f32x16 pa;
; #pragma unroll
;         for (int r = 0; r < 16; ++r) pa[r] = 0.f;
; #pragma unroll
;         for (int d0 = 0; d0 < 4; ++d0) { const bf16x8 a = *(const LAS bf16x8*)(kbase + kb * 32 * KSTR + d0 * 32); pa = __builtin_amdgcn_mfma_f32_32x32x16_bf16(a, qf[d0], pa, 0, 0, 0); }
;         if (BM == 0) {
;             const float cb = bth[512];
; #pragma unroll
;             for (int r = 0; r < 16; ++r) pa[r] += cb;
;         } else if (BM == 1) {
; #pragma unroll
;             for (int r = 0; r < 16; ++r) { int idx = ibase - 32 * kb - ((r & 3) + 8 * (r >> 2)); idx = idx > 512 ? 512 : idx; pa[r] += bth[idx]; }
;         } else {
;             const LAS float* bp = bth + (ibase - 32 * kb - 27);
; #pragma unroll
;             for (int r = 0; r < 16; ++r) pa[r] += bp[27 - ((r & 3) + 8 * (r >> 2))];
;         }
; #pragma unroll
;         for (int r = 0; r < 16; ++r) pa[r] = __builtin_amdgcn_exp2f(pa[r]);
;         if (SMASK) {
; #pragma unroll
;             for (int r = 0; r < 16; ++r) { const int key = 32 * kb + (r & 3) + 8 * (r >> 2) + 4 * h; if (key >= 16) pa[r] = 0.f; }
;         }
; #pragma unroll
;         for (int r = 0; r < 16; ++r) lsum += pa[r];
; #pragma unroll
;         for (int s = 0; s < 2; ++s) {
;             u32x4 pw; pw.x = pk2(pa[8 * s], pa[8 * s + 1]); pw.y = pk2(pa[8 * s + 2], pa[8 * s + 3]); pw.z = pk2(pa[8 * s + 4], pa[8 * s + 5]); pw.w = pk2(pa[8 * s + 6], pa[8 * s + 7]);
;             const bf16x8 pb = __builtin_bit_cast(bf16x8, pw);
;             const LAS unsigned char* va = vbase + (kb * 32 + 16 * s) * VSTR;
;             { const s16x4 lo = tr_read(va), hi = tr_read(va + 8 * VSTR); o0 = __builtin_amdgcn_mfma_f32_32x32x16_bf16(VFR(lo, hi), pb, o0, 0, 0, 0); }
;             { const s16x4 lo = tr_read(va + 64), hi = tr_read(va + 64 + 8 * VSTR); o1 = __builtin_amdgcn_mfma_f32_32x32x16_bf16(VFR(lo, hi), pb, o1, 0, 0, 0); }
;         }
;     }
; }
.LBB0_1211:
	s_andn2_b64 vcc, exec, s[8:9]
	s_cbranch_vccnz .LBB0_1189
	ds_read_b128 v[34:37], v179 offset:37888
	v_mov_b32_e32 v38, s21
	ds_read_b32 v66, v38 offset:2048
	s_nop 5
	ds_read_b128 v[50:53], v179 offset:37952
	ds_read_b128 v[54:57], v179 offset:37984
	s_waitcnt lgkmcnt(3)
	v_mfma_f32_32x32x16_bf16 v[34:49], v[34:37], v[82:85], 0
	v_mfma_f32_32x32x16_bf16 v[34:49], v[130:133], v[86:89], v[34:49]
	s_waitcnt lgkmcnt(1)
	v_mfma_f32_32x32x16_bf16 v[34:49], v[50:53], v[90:93], v[34:49]
	ds_read_b64_tr_b16 v[50:51], v171 offset:55296
	ds_read_b64_tr_b16 v[52:53], v171 offset:57856
	ds_read_b64_tr_b16 v[60:61], v171 offset:57920
	ds_read_b64_tr_b16 v[58:59], v171 offset:55360
	ds_read_b128 v[62:65], v179 offset:46592
	s_waitcnt lgkmcnt(5)
	v_mfma_f32_32x32x16_bf16 v[34:49], v[54:57], v[94:97], v[34:49]
	s_nop 11
	v_add_f32_e32 v34, v66, v34
	v_add_f32_e32 v35, v66, v35
	v_add_f32_e32 v36, v66, v36
	v_add_f32_e32 v37, v66, v37
	v_add_f32_e32 v38, v66, v38
	v_add_f32_e32 v39, v66, v39
	v_add_f32_e32 v40, v66, v40
	v_add_f32_e32 v41, v66, v41
	v_exp_f32_e32 v54, v34
	v_exp_f32_e32 v55, v35
	v_exp_f32_e32 v56, v36
	v_exp_f32_e32 v57, v37
	v_exp_f32_e32 v67, v38
	v_exp_f32_e32 v68, v39
	v_exp_f32_e32 v69, v40
	v_exp_f32_e32 v70, v41
	v_cvt_pk_bf16_f32 v34, v54, v55
	v_cvt_pk_bf16_f32 v35, v56, v57
	v_cvt_pk_bf16_f32 v36, v67, v68
	v_cvt_pk_bf16_f32 v37, v69, v70
	v_add_f32_e32 v42, v66, v42
	v_add_f32_e32 v43, v66, v43
	v_add_f32_e32 v44, v66, v44
	v_add_f32_e32 v45, v66, v45
	s_waitcnt lgkmcnt(3)
	v_mfma_f32_32x32x16_bf16 v[2:17], v[50:53], v[34:37], v[2:17]
	v_add_f32_e32 v38, v66, v46
	v_add_f32_e32 v39, v66, v47
	v_add_f32_e32 v40, v66, v48
	v_add_f32_e32 v41, v66, v49
	ds_read_b128 v[50:53], v179 offset:46624
	v_exp_f32_e32 v71, v42
	v_exp_f32_e32 v72, v43
	v_exp_f32_e32 v73, v44
	s_waitcnt lgkmcnt(2)
	v_mfma_f32_32x32x16_bf16 v[18:33], v[58:61], v[34:37], v[18:33]
	v_exp_f32_e32 v58, v45
	v_exp_f32_e32 v74, v38
	v_exp_f32_e32 v75, v39
	v_exp_f32_e32 v76, v40
	v_exp_f32_e32 v77, v41
	v_add_f32_e32 v54, v180, v54
	v_add_f32_e32 v54, v55, v54
	s_waitcnt lgkmcnt(1)
	v_mfma_f32_32x32x16_bf16 v[34:49], v[62:65], v[82:85], 0
	v_add_f32_e32 v54, v56, v54
	v_add_f32_e32 v54, v57, v54
	v_add_f32_e32 v54, v67, v54
	v_add_f32_e32 v54, v68, v54
	v_add_f32_e32 v59, v69, v54
	ds_read_b128 v[54:57], v179 offset:46656
	s_waitcnt lgkmcnt(1)
	v_mfma_f32_32x32x16_bf16 v[34:49], v[50:53], v[86:89], v[34:49]
	v_add_f32_e32 v50, v70, v59
	v_add_f32_e32 v50, v71, v50
	v_add_f32_e32 v50, v72, v50
	v_add_f32_e32 v50, v73, v50
	v_add_f32_e32 v50, v58, v50
	v_add_f32_e32 v59, v74, v50
	ds_read_b128 v[50:53], v179 offset:46688
	s_waitcnt lgkmcnt(1)
	v_mfma_f32_32x32x16_bf16 v[34:49], v[54:57], v[90:93], v[34:49]
	v_add_f32_e32 v54, v75, v59
	v_cvt_pk_bf16_f32 v55, v73, v58
	ds_read_b64_tr_b16 v[58:59], v171 offset:60416
	ds_read_b64_tr_b16 v[60:61], v171 offset:62976
	v_add_f32_e32 v54, v76, v54
	v_add_f32_e32 v62, v77, v54
	v_cvt_pk_bf16_f32 v54, v71, v72
	v_cvt_pk_bf16_f32 v56, v74, v75
	s_waitcnt lgkmcnt(2)
	v_mfma_f32_32x32x16_bf16 v[34:49], v[50:53], v[94:97], v[34:49]
	ds_read_b64_tr_b16 v[52:53], v171 offset:63040
	ds_read_b64_tr_b16 v[50:51], v171 offset:60480
	v_cvt_pk_bf16_f32 v57, v76, v77
	s_waitcnt lgkmcnt(2)
	s_nop 0
	v_mfma_f32_32x32x16_bf16 v[2:17], v[58:61], v[54:57], v[2:17]
	s_nop 5
	v_add_f32_e32 v34, v66, v34
	v_add_f32_e32 v35, v66, v35
	v_add_f32_e32 v36, v66, v36
	v_add_f32_e32 v37, v66, v37
	v_add_f32_e32 v38, v66, v38
	v_add_f32_e32 v39, v66, v39
	v_add_f32_e32 v40, v66, v40
	s_waitcnt lgkmcnt(0)
	v_mfma_f32_32x32x16_bf16 v[18:33], v[50:53], v[54:57], v[18:33]
	v_exp_f32_e32 v50, v34
	v_add_f32_e32 v41, v66, v41
	v_exp_f32_e32 v51, v35
	v_add_f32_e32 v42, v66, v42
	v_add_f32_e32 v43, v66, v43
	v_add_f32_e32 v44, v66, v44
	v_add_f32_e32 v45, v66, v45
	v_exp_f32_e32 v52, v36
	v_exp_f32_e32 v53, v37
	v_exp_f32_e32 v54, v38
	v_exp_f32_e32 v55, v39
	v_exp_f32_e32 v56, v40
	v_exp_f32_e32 v57, v41
	ds_read_b64_tr_b16 v[34:35], v174 offset:10240
	ds_read_b64_tr_b16 v[36:37], v174 offset:12800
	v_exp_f32_e32 v58, v42
	v_exp_f32_e32 v59, v43
	v_exp_f32_e32 v60, v44
	v_exp_f32_e32 v61, v45
	ds_read_b64_tr_b16 v[44:45], v174 offset:12864
	ds_read_b64_tr_b16 v[42:43], v174 offset:10304
	v_add_f32_e32 v38, v62, v50
	v_add_f32_e32 v38, v51, v38
	v_add_f32_e32 v62, v52, v38
	v_cvt_pk_bf16_f32 v38, v50, v51
	v_cvt_pk_bf16_f32 v39, v52, v53
	v_cvt_pk_bf16_f32 v40, v54, v55
	v_cvt_pk_bf16_f32 v41, v56, v57
	v_add_f32_e32 v46, v66, v46
	v_add_f32_e32 v47, v66, v47
	s_waitcnt lgkmcnt(2)
	v_mfma_f32_32x32x16_bf16 v[2:17], v[34:37], v[38:41], v[2:17]
	v_add_f32_e32 v34, v53, v62
	v_add_f32_e32 v34, v54, v34
	v_add_f32_e32 v34, v55, v34
	v_add_f32_e32 v48, v66, v48
	v_add_f32_e32 v49, v66, v49
	v_add_f32_e32 v34, v56, v34
	v_exp_f32_e32 v46, v46
	s_waitcnt lgkmcnt(0)
	v_mfma_f32_32x32x16_bf16 v[18:33], v[42:45], v[38:41], v[18:33]
	v_exp_f32_e32 v47, v47
	v_exp_f32_e32 v48, v48
	v_exp_f32_e32 v49, v49
	v_add_f32_e32 v50, v57, v34
	ds_read_b64_tr_b16 v[34:35], v174 offset:15360
	ds_read_b64_tr_b16 v[36:37], v174 offset:17920
	ds_read_b64_tr_b16 v[44:45], v174 offset:17984
	ds_read_b64_tr_b16 v[42:43], v174 offset:15424
	v_cvt_pk_bf16_f32 v38, v58, v59
	v_cvt_pk_bf16_f32 v39, v60, v61
	v_cvt_pk_bf16_f32 v40, v46, v47
	v_cvt_pk_bf16_f32 v41, v48, v49
	v_add_f32_e32 v50, v58, v50
	s_waitcnt lgkmcnt(2)
	v_mfma_f32_32x32x16_bf16 v[2:17], v[34:37], v[38:41], v[2:17]
	v_add_f32_e32 v34, v59, v50
	v_add_f32_e32 v34, v60, v34
	v_add_f32_e32 v34, v61, v34
	v_add_f32_e32 v34, v46, v34
	v_add_f32_e32 v34, v47, v34
	v_add_f32_e32 v34, v48, v34
	v_add_f32_e32 v66, v49, v34
	s_waitcnt lgkmcnt(0)
	v_mfma_f32_32x32x16_bf16 v[18:33], v[42:45], v[38:41], v[18:33]
	v_mov_b32_e32 v180, v66
	s_branch .Lmy_att_j2

; #define LAS __attribute__((address_space(3)))
; DI void sgu_load(const Params& p, int uid, int tid, SguRegs& R) {
;     ...
;     const int ib = w & 3, iloc = 32 * ib + r32;
;     R.bsv = p.in[22][g * 128 + iloc];
; }
; DI void sgu_unit(const Params& p, LAS unsigned char* lds, int uid, int tid, const SguRegs& C, bool has_next, int uid_next, SguRegs& R) {
;     const int b = uid >> 7, ch = (uid >> 2) & 31, g = uid & 3;
;     const int lane = tid & 63, w = __builtin_amdgcn_readfirstlane(tid >> 6), r32 = lane & 31, h = lane >> 5;
;     bf16_t* CAT = (bf16_t*)(p.ws + WS_CAT);
;     const float* sw = p.in[21];
;     const size_t r0 = (size_t)b * SEQ + ch * 128;
;     const int ib = w & 3, dh = w >> 2, iloc = 32 * ib + r32;
;     const size_t row = r0 + iloc;
;     const float* Wrow = sw + ((size_t)g * 128 + iloc) * 128 + 8 * h;
;     f32x4 wv[8][2];
; #pragma unroll
;     for (int js = 0; js < 8; ++js) { if (js <= 2 * ib + 1) { wv[js][0] = *(const f32x4*)(Wrow + 16 * js); wv[js][1] = *(const f32x4*)(Wrow + 16 * js + 4); } else { wv[js][0] = (f32x4){0.f, 0.f, 0.f, 0.f}; wv[js][1] = wv[js][0]; } }
; DI void sgu_all(const Params& p, LAS unsigned char* lds, int first, int stride) {
;     int tid_ = threadIdx.x; asm volatile("" : "+v"(tid_));
;     const int tid = tid_;
;     __syncthreads();
;     { LAS float* lnp = (LAS float*)(lds + SG_LN); lnp[tid] = p.in[19][tid]; lnp[512 + tid] = p.in[20][tid]; }
;     if (first >= 1024) { __syncthreads(); return; }
;     SguRegs R; sgu_load(p, first, tid, R);
;     for (int uid = first; uid < 1024; uid += stride) {
;         const SguRegs C = R;
;         sgu_unit(p, lds, uid, tid, C, uid + stride < 1024, uid + stride, R);
.LBB0_1235:
	s_waitcnt lgkmcnt(0)
	v_ashrrev_i32_e32 v149, 31, v148
	v_lshlrev_b64 v[2:3], 2, v[148:149]
	v_lshl_add_u64 v[4:5], s[42:43], 0, v[2:3]
	v_lshl_add_u64 v[2:3], s[44:45], 0, v[2:3]
	s_barrier
	global_load_dword v4, v[4:5], off
	v_readlane_b32 s6, v247, 3
	global_load_dword v2, v[2:3], off
	v_readlane_b32 s7, v247, 4
	s_mov_b32 s5, 0
	s_mov_b64 s[0:1], -1
	s_and_b64 vcc, exec, s[6:7]
	v_lshl_add_u32 v3, v148, 2, 0
	s_waitcnt vmcnt(0)
	ds_write2st64_b32 v3, v4, v2 offset0:192 offset1:200
	s_cbranch_vccz .LBB0_1265
	v_ashrrev_i32_e32 v146, 2, v148
	v_readlane_b32 s10, v247, 9
	v_ashrrev_i32_e32 v147, 31, v146
	v_readlane_b32 s11, v247, 10
	v_mov_b32_e32 v151, 0
	v_mov_b32_e32 v153, v151
	v_lshl_add_u64 v[2:3], s[10:11], 0, v[146:147]
	v_readlane_b32 s10, v247, 7
	v_lshlrev_b64 v[4:5], 6, v[2:3]
	v_readlane_b32 s11, v247, 8
	v_lshlrev_b64 v[2:3], 10, v[2:3]
	s_movk_i32 s1, 0x60
	v_lshl_add_u64 v[14:15], s[10:11], 0, v[4:5]
	v_readlane_b32 s10, v247, 11
	v_lshlrev_b32_e32 v4, 5, v148
	v_readlane_b32 s11, v247, 12
	v_and_b32_e32 v16, 0x60, v4
	v_lshlrev_b32_e32 v152, 1, v16
	v_lshl_add_u64 v[2:3], s[10:11], 0, v[2:3]
	v_lshl_add_u64 v[18:19], v[2:3], 0, v[152:153]
	global_load_dwordx4 v[30:33], v[14:15], off offset:48
	global_load_dwordx4 v[26:29], v[14:15], off offset:32
	global_load_dwordx4 v[138:141], v[14:15], off offset:16
	global_load_dwordx4 v[142:145], v[14:15], off
	global_load_dwordx4 v[2:5], v[18:19], off offset:48
	global_load_dwordx4 v[6:9], v[18:19], off offset:32
	global_load_dwordx4 v[10:13], v[18:19], off offset:16
	global_load_dwordx4 v[22:25], v[18:19], off
	v_and_b32_e32 v149, 31, v148
	v_lshrrev_b32_e32 v14, 1, v148
	v_and_or_b32 v153, v14, s1, v149
	v_readlane_b32 s1, v247, 5
	s_lshl_b32 s0, s85, 14
	s_lshl_b32 s6, s84, 1
	v_or_b32_e32 v15, s1, v153
	v_lshlrev_b32_e32 v15, 2, v15
	global_load_dword v156, v15, s[48:49]
	v_lshrrev_b32_e32 v15, 2, v148
	v_and_b32_e32 v157, 8, v15
	s_movk_i32 s1, 0x140
	v_and_b32_e32 v15, 11, v15
	v_mad_u32_u24 v165, v15, s1, 0
	v_lshlrev_b32_e32 v15, 2, v148
	v_and_b32_e32 v15, 12, v15
	v_and_b32_e32 v154, 16, v14
	v_mul_lo_u32 v14, v146, s1
	v_and_or_b32 v166, v148, 16, v15
	v_or_b32_e32 v15, s84, v16
	s_add_u32 s8, s50, s6
	v_add_u32_e32 v164, 0, v14
	v_or_b32_e32 v14, 16, v152
	v_or_b32_e32 v17, 32, v152
	v_or_b32_e32 v18, 48, v152
	v_lshl_add_u32 v229, v15, 2, 0
	v_add_u32_e32 v15, s84, v16
	v_lshlrev_b32_e32 v150, 2, v157
	s_addc_u32 s9, s51, 0
	v_mov_b32_e32 v155, v151
	v_or_b32_e32 v167, 4, v157
	v_or_b32_e32 v168, 5, v157
	v_or_b32_e32 v169, 2, v157
	v_or_b32_e32 v170, 6, v157
	v_or_b32_e32 v171, 3, v157
	v_or_b32_e32 v172, 7, v157
	v_or_b32_e32 v173, 16, v157
	v_or_b32_e32 v174, 20, v157
	v_or_b32_e32 v175, 17, v157
	v_or_b32_e32 v176, 21, v157
	v_or_b32_e32 v177, 18, v157
	v_or_b32_e32 v178, 22, v157
	v_or_b32_e32 v179, 19, v157
	v_or_b32_e32 v180, 23, v157
	v_or_b32_e32 v181, 32, v157
	v_or_b32_e32 v182, 36, v157
	v_or_b32_e32 v183, 33, v157
	v_or_b32_e32 v184, 37, v157
	v_or_b32_e32 v185, 34, v157
	v_or_b32_e32 v186, 38, v157
	v_or_b32_e32 v187, 35, v157
	v_or_b32_e32 v188, 39, v157
	v_or_b32_e32 v189, 48, v157
	v_or_b32_e32 v190, 52, v157
	v_or_b32_e32 v191, 49, v157
	v_or_b32_e32 v192, 53, v157
	v_or_b32_e32 v193, 50, v157
	v_or_b32_e32 v194, 54, v157
	v_or_b32_e32 v195, 51, v157
	v_or_b32_e32 v196, 55, v157
	v_or_b32_e32 v197, 64, v157
	v_or_b32_e32 v198, 0x44, v157
	v_or_b32_e32 v199, 0x41, v157
	v_or_b32_e32 v200, 0x45, v157
	v_or_b32_e32 v201, 0x42, v157
	v_or_b32_e32 v202, 0x46, v157
	v_or_b32_e32 v203, 0x43, v157
	v_or_b32_e32 v204, 0x47, v157
	v_or_b32_e32 v205, 0x50, v157
	v_or_b32_e32 v206, 0x54, v157
	v_or_b32_e32 v207, 0x51, v157
	v_or_b32_e32 v208, 0x55, v157
	v_or_b32_e32 v209, 0x52, v157
	v_or_b32_e32 v210, 0x56, v157
	v_or_b32_e32 v211, 0x53, v157
	v_or_b32_e32 v212, 0x57, v157
	v_or_b32_e32 v213, 0x60, v157
	v_or_b32_e32 v214, 0x64, v157
	v_or_b32_e32 v215, 0x61, v157
	v_or_b32_e32 v216, 0x65, v157
	v_or_b32_e32 v217, 0x62, v157
	v_or_b32_e32 v218, 0x66, v157
	v_or_b32_e32 v219, 0x63, v157
	v_or_b32_e32 v220, 0x67, v157
	v_or_b32_e32 v221, 0x70, v157
	v_or_b32_e32 v222, 0x74, v157
	v_or_b32_e32 v223, 0x71, v157
	v_or_b32_e32 v224, 0x75, v157
	v_or_b32_e32 v225, 0x72, v157
	v_or_b32_e32 v226, 0x76, v157
	v_or_b32_e32 v227, 0x73, v157
	v_or_b32_e32 v228, 0x77, v157
	v_lshl_add_u32 v230, v15, 2, 0
	v_lshl_add_u64 v[158:159], s[46:47], 0, v[150:151]
	s_lshl_b32 s11, s0, 2
	v_lshlrev_b32_e32 v160, 1, v16
	s_mov_b32 s10, 0x3b000000
	s_mov_b32 s12, 0x800000
	v_add_u32_e32 v231, v164, v14
	v_add_u32_e32 v232, v164, v17
	v_add_u32_e32 v233, v164, v18
	s_mov_b64 s[18:19], 0x11c00400
	s_mov_b32 s13, 0x11c00000
	s_mov_b32 s7, s5
	s_mov_b32 s4, s2
	v_readfirstlane_b32 s22, v148
	s_bfe_u32 s98, s22, 0x20006
	s_bfe_u32 s22, s22, 0x10008
	s_mul_i32 s22, s22, 0xa000
	s_add_i32 s99, s98, 1
	s_mul_i32 s99, s99, s98
	s_lshl_b32 s99, s99, 11
	s_add_i32 s99, s99, s22
	s_add_i32 s99, s99, 0xd000
	v_and_b32_e32 v248, 63, v148
	v_lshl_add_u32 v248, v248, 4, s99
	v_lshl_or_b32 v250, s98, 5, v149
	v_lshl_or_b32 v250, v250, 9, s11
	v_mov_b32_e32 v251, 0
	v_lshl_add_u64 v[250:251], v[158:159], 0, v[250:251]
	global_load_dwordx4 v[14:17], v[250:251], off offset:16
	global_load_dwordx4 v[18:21], v[250:251], off
	global_load_dwordx4 v[130:133], v[250:251], off offset:80
	global_load_dwordx4 v[134:137], v[250:251], off offset:64
	s_cmp_eq_u32 s98, 0
	s_cbranch_scc1 .Lmy_wc_ld_done
	global_load_dwordx4 v[118:121], v[250:251], off offset:144
	global_load_dwordx4 v[126:129], v[250:251], off offset:128
	global_load_dwordx4 v[110:113], v[250:251], off offset:208
	global_load_dwordx4 v[122:125], v[250:251], off offset:192
	s_cmp_lt_u32 s98, 2
	s_cbranch_scc1 .Lmy_wc_ld_done
	global_load_dwordx4 v[94:97], v[250:251], off offset:272
	global_load_dwordx4 v[114:117], v[250:251], off offset:256
	global_load_dwordx4 v[102:105], v[250:251], off offset:336
	global_load_dwordx4 v[106:109], v[250:251], off offset:320
	s_cmp_lg_u32 s98, 3
	s_cbranch_scc1 .Lmy_wc_ld_done
	global_load_dwordx4 v[78:81], v[250:251], off offset:384
	global_load_dwordx4 v[98:101], v[250:251], off offset:400
	global_load_dwordx4 v[90:93], v[250:251], off offset:448
	global_load_dwordx4 v[86:89], v[250:251], off offset:464
